# GEMM loops: M0 write moved ahead of the DMA address add so the add supplies the wait state (32 s_nop removed)
# speedup vs baseline: 1.0405x; 1.0002x over previous
.LBB0_177:
	ds_read_b128 v[128:131], v171
	ds_read_b128 v[132:135], v171 offset:1024
	ds_read_b128 v[136:139], v171 offset:2048
	ds_read_b128 v[160:163], v171 offset:3072
	ds_read_b128 v[164:167], v172
	ds_read_b128 v[174:177], v172 offset:1024
	ds_read_b128 v[178:181], v172 offset:2048
	ds_read_b128 v[182:185], v172 offset:3072
	s_add_u32 s52, s44, 0xfffc0080
	s_addc_u32 s53, s45, -1
	s_cmp_eq_u32 s84, 12
	s_cselect_b32 s57, s7, s53
	s_cselect_b32 s56, s8, s52
	s_cselect_b32 s53, s27, s83
	s_cselect_b32 s52, s29, s43
	v_lshl_add_u64 v[198:199], s[44:45], 0, v[152:153]
	s_add_i32 m0, s33, 0xc000
	ds_read_b128 v[186:189], v173
	ds_read_b128 v[190:193], v173 offset:1024
	ds_read_b128 v[194:197], v173 offset:2048
	ds_read_b128 v[202:205], v173 offset:3072
	ds_read_b128 v[206:209], v173 offset:4096
	ds_read_b128 v[210:213], v173 offset:5120
	ds_read_b128 v[214:217], v173 offset:6144
	ds_read_b128 v[218:221], v173 offset:7168
	global_load_lds_dwordx4 v[198:199], off
	s_add_i32 m0, s33, 0xe000
	v_lshl_add_u64 v[198:199], s[44:45], 0, v[154:155]
	global_load_lds_dwordx4 v[198:199], off
	s_waitcnt vmcnt(8)
	s_waitcnt lgkmcnt(0)
	s_barrier
	s_waitcnt lgkmcnt(0)
	v_mfma_f32_16x16x32_bf16 v[124:127], v[128:131], v[186:189], v[124:127]
	v_mfma_f32_16x16x32_bf16 v[120:123], v[136:139], v[186:189], v[120:123]
	v_mfma_f32_16x16x32_bf16 v[112:115], v[128:131], v[194:197], v[112:115]
	v_mfma_f32_16x16x32_bf16 v[104:107], v[136:139], v[194:197], v[104:107]
	v_mfma_f32_16x16x32_bf16 v[100:103], v[128:131], v[206:209], v[100:103]
	v_mfma_f32_16x16x32_bf16 v[92:95], v[136:139], v[206:209], v[92:95]
	v_mfma_f32_16x16x32_bf16 v[84:87], v[128:131], v[214:217], v[84:87]
	v_mfma_f32_16x16x32_bf16 v[76:79], v[136:139], v[214:217], v[76:79]
	v_mfma_f32_16x16x32_bf16 v[124:127], v[132:135], v[190:193], v[124:127]
	v_mfma_f32_16x16x32_bf16 v[120:123], v[160:163], v[190:193], v[120:123]
	v_mfma_f32_16x16x32_bf16 v[112:115], v[132:135], v[202:205], v[112:115]
	v_mfma_f32_16x16x32_bf16 v[104:107], v[160:163], v[202:205], v[104:107]
	v_mfma_f32_16x16x32_bf16 v[100:103], v[132:135], v[210:213], v[100:103]
	v_mfma_f32_16x16x32_bf16 v[92:95], v[160:163], v[210:213], v[92:95]
	v_mfma_f32_16x16x32_bf16 v[84:87], v[132:135], v[218:221], v[84:87]
	v_mfma_f32_16x16x32_bf16 v[76:79], v[160:163], v[218:221], v[76:79]
	v_mfma_f32_16x16x32_bf16 v[116:119], v[164:167], v[186:189], v[116:119]
	v_mfma_f32_16x16x32_bf16 v[108:111], v[178:181], v[186:189], v[108:111]
	v_mfma_f32_16x16x32_bf16 v[96:99], v[164:167], v[194:197], v[96:99]
	v_mfma_f32_16x16x32_bf16 v[88:91], v[178:181], v[194:197], v[88:91]
	v_mfma_f32_16x16x32_bf16 v[80:83], v[164:167], v[206:209], v[80:83]
	v_mfma_f32_16x16x32_bf16 v[72:75], v[178:181], v[206:209], v[72:75]
	v_mfma_f32_16x16x32_bf16 v[68:71], v[164:167], v[214:217], v[68:71]
	v_mfma_f32_16x16x32_bf16 v[64:67], v[178:181], v[214:217], v[64:67]
	v_mfma_f32_16x16x32_bf16 v[116:119], v[174:177], v[190:193], v[116:119]
	v_mfma_f32_16x16x32_bf16 v[108:111], v[182:185], v[190:193], v[108:111]
	v_mfma_f32_16x16x32_bf16 v[96:99], v[174:177], v[202:205], v[96:99]
	v_mfma_f32_16x16x32_bf16 v[88:91], v[182:185], v[202:205], v[88:91]
	v_mfma_f32_16x16x32_bf16 v[80:83], v[174:177], v[210:213], v[80:83]
	v_mfma_f32_16x16x32_bf16 v[72:75], v[182:185], v[210:213], v[72:75]
	v_mfma_f32_16x16x32_bf16 v[68:71], v[174:177], v[218:221], v[68:71]
	v_mfma_f32_16x16x32_bf16 v[64:67], v[182:185], v[218:221], v[64:67]
	s_barrier
	s_add_i32 s85, s80, s3
	v_lshl_add_u64 v[198:199], s[52:53], 0, v[142:143]
	s_mov_b32 m0, s85
	ds_read_b128 v[186:189], v173 offset:16384
	ds_read_b128 v[190:193], v173 offset:17408
	ds_read_b128 v[194:197], v173 offset:18432
	ds_read_b128 v[202:205], v173 offset:19456
	ds_read_b128 v[206:209], v173 offset:20480
	ds_read_b128 v[210:213], v173 offset:21504
	ds_read_b128 v[214:217], v173 offset:22528
	ds_read_b128 v[218:221], v173 offset:23552
	global_load_lds_dwordx4 v[198:199], off
	s_add_i32 m0, s85, 0x2000
	s_add_u32 s86, s52, 0x40000
	v_lshl_add_u64 v[200:201], s[52:53], 0, v[146:147]
	s_addc_u32 s87, s53, 0
	s_add_i32 s85, s81, s3
	global_load_lds_dwordx4 v[200:201], off
	v_lshl_add_u64 v[222:223], s[86:87], 0, v[142:143]
	s_mov_b32 m0, s85
	v_lshl_add_u64 v[224:225], s[56:57], 0, v[144:145]
	global_load_lds_dwordx4 v[222:223], off
	s_add_i32 m0, s85, 0x2000
	v_lshl_add_u64 v[222:223], s[86:87], 0, v[146:147]
	global_load_lds_dwordx4 v[222:223], off
	s_mov_b32 m0, s33
	v_lshl_add_u64 v[222:223], s[56:57], 0, v[140:141]
	global_load_lds_dwordx4 v[222:223], off
	s_mov_b32 m0, s62
	s_nop 0
	global_load_lds_dwordx4 v[224:225], off
	s_waitcnt vmcnt(8)
	s_waitcnt lgkmcnt(0)
	s_barrier
	s_waitcnt lgkmcnt(0)
	v_mfma_f32_16x16x32_bf16 v[60:63], v[128:131], v[186:189], v[60:63]
	v_mfma_f32_16x16x32_bf16 v[56:59], v[136:139], v[186:189], v[56:59]
	v_mfma_f32_16x16x32_bf16 v[52:55], v[128:131], v[194:197], v[52:55]
	v_mfma_f32_16x16x32_bf16 v[44:47], v[136:139], v[194:197], v[44:47]
	v_mfma_f32_16x16x32_bf16 v[36:39], v[128:131], v[206:209], v[36:39]
	v_mfma_f32_16x16x32_bf16 v[28:31], v[136:139], v[206:209], v[28:31]
	v_mfma_f32_16x16x32_bf16 v[20:23], v[128:131], v[214:217], v[20:23]
	v_mfma_f32_16x16x32_bf16 v[12:15], v[136:139], v[214:217], v[12:15]
	v_mfma_f32_16x16x32_bf16 v[60:63], v[132:135], v[190:193], v[60:63]
	v_mfma_f32_16x16x32_bf16 v[56:59], v[160:163], v[190:193], v[56:59]
	v_mfma_f32_16x16x32_bf16 v[52:55], v[132:135], v[202:205], v[52:55]
	v_mfma_f32_16x16x32_bf16 v[44:47], v[160:163], v[202:205], v[44:47]
	v_mfma_f32_16x16x32_bf16 v[36:39], v[132:135], v[210:213], v[36:39]
	v_mfma_f32_16x16x32_bf16 v[28:31], v[160:163], v[210:213], v[28:31]
	v_mfma_f32_16x16x32_bf16 v[20:23], v[132:135], v[218:221], v[20:23]
	v_mfma_f32_16x16x32_bf16 v[12:15], v[160:163], v[218:221], v[12:15]
	v_mfma_f32_16x16x32_bf16 v[48:51], v[164:167], v[186:189], v[48:51]
	v_mfma_f32_16x16x32_bf16 v[40:43], v[178:181], v[186:189], v[40:43]
	v_mfma_f32_16x16x32_bf16 v[32:35], v[164:167], v[194:197], v[32:35]
	v_mfma_f32_16x16x32_bf16 v[24:27], v[178:181], v[194:197], v[24:27]
	v_mfma_f32_16x16x32_bf16 v[16:19], v[164:167], v[206:209], v[16:19]
	v_mfma_f32_16x16x32_bf16 v[8:11], v[178:181], v[206:209], v[8:11]
	v_mfma_f32_16x16x32_bf16 v[4:7], v[164:167], v[214:217], v[4:7]
	v_mfma_f32_16x16x32_bf16 v[0:3], v[178:181], v[214:217], v[0:3]
	v_mfma_f32_16x16x32_bf16 v[48:51], v[174:177], v[190:193], v[48:51]
	v_mfma_f32_16x16x32_bf16 v[40:43], v[182:185], v[190:193], v[40:43]
	v_mfma_f32_16x16x32_bf16 v[32:35], v[174:177], v[202:205], v[32:35]
	v_mfma_f32_16x16x32_bf16 v[24:27], v[182:185], v[202:205], v[24:27]
	v_mfma_f32_16x16x32_bf16 v[16:19], v[174:177], v[210:213], v[16:19]
	v_mfma_f32_16x16x32_bf16 v[8:11], v[182:185], v[210:213], v[8:11]
	v_mfma_f32_16x16x32_bf16 v[4:7], v[174:177], v[218:221], v[4:7]
	v_mfma_f32_16x16x32_bf16 v[0:3], v[182:185], v[218:221], v[0:3]
	s_barrier
	s_add_i32 s85, 0, 0x18000
	v_add_u32_e32 v148, s85, v169
	s_add_i32 s86, 0, 0x1c000
	ds_read_b128 v[128:131], v148
	ds_read_b128 v[132:135], v148 offset:1024
	ds_read_b128 v[136:139], v148 offset:2048
	ds_read_b128 v[160:163], v148 offset:3072
	v_add_u32_e32 v148, s86, v169
	ds_read_b128 v[164:167], v148
	ds_read_b128 v[174:177], v148 offset:1024
	ds_read_b128 v[178:181], v148 offset:2048
	ds_read_b128 v[182:185], v148 offset:3072
	s_add_u32 s56, s56, 0x40000
	s_addc_u32 s57, s57, 0
	s_mov_b32 m0, s63
	v_lshl_add_u64 v[226:227], s[56:57], 0, v[140:141]
	ds_read_b128 v[186:189], v173 offset:32768
	ds_read_b128 v[190:193], v173 offset:33792
	ds_read_b128 v[194:197], v173 offset:34816
	ds_read_b128 v[202:205], v173 offset:35840
	ds_read_b128 v[206:209], v173 offset:36864
	ds_read_b128 v[210:213], v173 offset:37888
	ds_read_b128 v[214:217], v173 offset:38912
	ds_read_b128 v[218:221], v173 offset:39936
	global_load_lds_dwordx4 v[226:227], off
	s_mov_b32 m0, s64
	v_lshl_add_u64 v[226:227], s[56:57], 0, v[144:145]
	global_load_lds_dwordx4 v[226:227], off
	s_waitcnt vmcnt(8)
	s_waitcnt lgkmcnt(0)
	s_barrier
	s_waitcnt lgkmcnt(0)
	v_mfma_f32_16x16x32_bf16 v[124:127], v[128:131], v[186:189], v[124:127]
	v_mfma_f32_16x16x32_bf16 v[120:123], v[136:139], v[186:189], v[120:123]
	v_mfma_f32_16x16x32_bf16 v[112:115], v[128:131], v[194:197], v[112:115]
	v_mfma_f32_16x16x32_bf16 v[104:107], v[136:139], v[194:197], v[104:107]
	v_mfma_f32_16x16x32_bf16 v[100:103], v[128:131], v[206:209], v[100:103]
	v_mfma_f32_16x16x32_bf16 v[92:95], v[136:139], v[206:209], v[92:95]
	v_mfma_f32_16x16x32_bf16 v[84:87], v[128:131], v[214:217], v[84:87]
	v_mfma_f32_16x16x32_bf16 v[76:79], v[136:139], v[214:217], v[76:79]
	v_mfma_f32_16x16x32_bf16 v[124:127], v[132:135], v[190:193], v[124:127]
	v_mfma_f32_16x16x32_bf16 v[120:123], v[160:163], v[190:193], v[120:123]
	v_mfma_f32_16x16x32_bf16 v[112:115], v[132:135], v[202:205], v[112:115]
	v_mfma_f32_16x16x32_bf16 v[104:107], v[160:163], v[202:205], v[104:107]
	v_mfma_f32_16x16x32_bf16 v[100:103], v[132:135], v[210:213], v[100:103]
	v_mfma_f32_16x16x32_bf16 v[92:95], v[160:163], v[210:213], v[92:95]
	v_mfma_f32_16x16x32_bf16 v[84:87], v[132:135], v[218:221], v[84:87]
	v_mfma_f32_16x16x32_bf16 v[76:79], v[160:163], v[218:221], v[76:79]
	v_mfma_f32_16x16x32_bf16 v[116:119], v[164:167], v[186:189], v[116:119]
	v_mfma_f32_16x16x32_bf16 v[108:111], v[178:181], v[186:189], v[108:111]
	v_mfma_f32_16x16x32_bf16 v[96:99], v[164:167], v[194:197], v[96:99]
	v_mfma_f32_16x16x32_bf16 v[88:91], v[178:181], v[194:197], v[88:91]
	v_mfma_f32_16x16x32_bf16 v[80:83], v[164:167], v[206:209], v[80:83]
	v_mfma_f32_16x16x32_bf16 v[72:75], v[178:181], v[206:209], v[72:75]
	v_mfma_f32_16x16x32_bf16 v[68:71], v[164:167], v[214:217], v[68:71]
	v_mfma_f32_16x16x32_bf16 v[64:67], v[178:181], v[214:217], v[64:67]
	v_mfma_f32_16x16x32_bf16 v[116:119], v[174:177], v[190:193], v[116:119]
	v_mfma_f32_16x16x32_bf16 v[108:111], v[182:185], v[190:193], v[108:111]
	v_mfma_f32_16x16x32_bf16 v[96:99], v[174:177], v[202:205], v[96:99]
	v_mfma_f32_16x16x32_bf16 v[88:91], v[182:185], v[202:205], v[88:91]
	v_mfma_f32_16x16x32_bf16 v[80:83], v[174:177], v[210:213], v[80:83]
	v_mfma_f32_16x16x32_bf16 v[72:75], v[182:185], v[210:213], v[72:75]
	v_mfma_f32_16x16x32_bf16 v[68:71], v[174:177], v[218:221], v[68:71]
	v_mfma_f32_16x16x32_bf16 v[64:67], v[182:185], v[218:221], v[64:67]
	s_barrier
	s_add_i32 s56, s85, s3
	v_lshl_add_u64 v[198:199], v[198:199], 0, s[16:17]
	s_mov_b32 m0, s56
	ds_read_b128 v[186:189], v173 offset:49152
	ds_read_b128 v[190:193], v173 offset:50176
	ds_read_b128 v[194:197], v173 offset:51200
	ds_read_b128 v[202:205], v173 offset:52224
	ds_read_b128 v[206:209], v173 offset:53248
	ds_read_b128 v[210:213], v173 offset:54272
	ds_read_b128 v[214:217], v173 offset:55296
	ds_read_b128 v[218:221], v173 offset:56320
	global_load_lds_dwordx4 v[198:199], off
	s_add_i32 m0, s56, 0x2000
	s_add_u32 s52, s52, 0x40080
	v_lshl_add_u64 v[198:199], v[200:201], 0, s[16:17]
	s_addc_u32 s53, s53, 0
	s_add_i32 s56, s86, s3
	global_load_lds_dwordx4 v[198:199], off
	s_mov_b32 m0, s56
	v_lshl_add_u64 v[198:199], s[52:53], 0, v[142:143]
	global_load_lds_dwordx4 v[198:199], off
	s_add_i32 m0, s56, 0x2000
	v_lshl_add_u64 v[198:199], s[52:53], 0, v[146:147]
	global_load_lds_dwordx4 v[198:199], off
	s_mov_b32 m0, s69
	v_lshl_add_u64 v[198:199], v[222:223], 0, s[16:17]
	global_load_lds_dwordx4 v[198:199], off
	s_mov_b32 m0, s72
	v_lshl_add_u64 v[198:199], v[224:225], 0, s[16:17]
	global_load_lds_dwordx4 v[198:199], off
	s_waitcnt vmcnt(8)
	s_waitcnt lgkmcnt(0)
	s_barrier
	s_waitcnt lgkmcnt(0)
	v_mfma_f32_16x16x32_bf16 v[60:63], v[128:131], v[186:189], v[60:63]
	v_mfma_f32_16x16x32_bf16 v[56:59], v[136:139], v[186:189], v[56:59]
	v_mfma_f32_16x16x32_bf16 v[52:55], v[128:131], v[194:197], v[52:55]
	v_mfma_f32_16x16x32_bf16 v[44:47], v[136:139], v[194:197], v[44:47]
	v_mfma_f32_16x16x32_bf16 v[36:39], v[128:131], v[206:209], v[36:39]
	v_mfma_f32_16x16x32_bf16 v[28:31], v[136:139], v[206:209], v[28:31]
	v_mfma_f32_16x16x32_bf16 v[20:23], v[128:131], v[214:217], v[20:23]
	v_mfma_f32_16x16x32_bf16 v[12:15], v[136:139], v[214:217], v[12:15]
	v_mfma_f32_16x16x32_bf16 v[60:63], v[132:135], v[190:193], v[60:63]
	v_mfma_f32_16x16x32_bf16 v[56:59], v[160:163], v[190:193], v[56:59]
	v_mfma_f32_16x16x32_bf16 v[52:55], v[132:135], v[202:205], v[52:55]
	v_mfma_f32_16x16x32_bf16 v[44:47], v[160:163], v[202:205], v[44:47]
	v_mfma_f32_16x16x32_bf16 v[36:39], v[132:135], v[210:213], v[36:39]
	v_mfma_f32_16x16x32_bf16 v[28:31], v[160:163], v[210:213], v[28:31]
	v_mfma_f32_16x16x32_bf16 v[20:23], v[132:135], v[218:221], v[20:23]
	v_mfma_f32_16x16x32_bf16 v[12:15], v[160:163], v[218:221], v[12:15]
	v_mfma_f32_16x16x32_bf16 v[48:51], v[164:167], v[186:189], v[48:51]
	v_mfma_f32_16x16x32_bf16 v[40:43], v[178:181], v[186:189], v[40:43]
	v_mfma_f32_16x16x32_bf16 v[32:35], v[164:167], v[194:197], v[32:35]
	v_mfma_f32_16x16x32_bf16 v[24:27], v[178:181], v[194:197], v[24:27]
	v_mfma_f32_16x16x32_bf16 v[16:19], v[164:167], v[206:209], v[16:19]
	v_mfma_f32_16x16x32_bf16 v[8:11], v[178:181], v[206:209], v[8:11]
	v_mfma_f32_16x16x32_bf16 v[4:7], v[164:167], v[214:217], v[4:7]
	v_mfma_f32_16x16x32_bf16 v[0:3], v[178:181], v[214:217], v[0:3]
	v_mfma_f32_16x16x32_bf16 v[48:51], v[174:177], v[190:193], v[48:51]
	v_mfma_f32_16x16x32_bf16 v[40:43], v[182:185], v[190:193], v[40:43]
	v_mfma_f32_16x16x32_bf16 v[32:35], v[174:177], v[202:205], v[32:35]
	v_mfma_f32_16x16x32_bf16 v[24:27], v[182:185], v[202:205], v[24:27]
	v_mfma_f32_16x16x32_bf16 v[16:19], v[174:177], v[210:213], v[16:19]
	v_mfma_f32_16x16x32_bf16 v[8:11], v[182:185], v[210:213], v[8:11]
	v_mfma_f32_16x16x32_bf16 v[4:7], v[174:177], v[218:221], v[4:7]
	v_mfma_f32_16x16x32_bf16 v[0:3], v[182:185], v[218:221], v[0:3]
	s_barrier
	s_add_i32 s84, s84, 2
	s_add_u32 s44, s44, 0x100
	s_addc_u32 s45, s45, 0
	s_add_u32 s43, s43, 0x100
	s_addc_u32 s83, s83, 0
	s_cmp_gt_u32 s84, 13
	s_cbranch_scc0 .LBB0_177
	s_and_b64 vcc, exec, s[18:19]
	s_cbranch_vccz .LBB0_180
	s_barrier

.LBB0_497:
	s_waitcnt lgkmcnt(0)
	ds_read_b128 v[0:3], v147
	ds_read_b128 v[4:7], v147 offset:1024
	ds_read_b128 v[8:11], v147 offset:2048
	ds_read_b128 v[12:15], v147 offset:3072
	ds_read_b128 v[16:19], v148
	ds_read_b128 v[20:23], v148 offset:1024
	ds_read_b128 v[24:27], v148 offset:2048
	ds_read_b128 v[28:31], v148 offset:3072
	s_ashr_i32 s49, s48, 31
	s_lshl_b64 s[50:51], s[48:49], 17
	s_add_u32 s50, s68, s50
	s_addc_u32 s51, s69, s51
	s_and_b64 s[52:53], s[8:9], exec
	s_cselect_b32 s65, s51, s59
	s_cselect_b32 s64, s50, s58
	s_ashr_i32 s45, s44, 31
	s_lshl_b64 s[52:53], s[44:45], 17
	s_add_u32 s52, s72, s52
	s_addc_u32 s53, s73, s53
	s_and_b64 s[62:63], s[8:9], exec
	s_cselect_b32 s63, s53, s61
	s_cselect_b32 s62, s52, s60
	s_add_u32 s92, s58, 0x10080
	s_addc_u32 s93, s59, 0
	s_add_i32 s94, s81, 0xc000
	v_lshl_add_u64 v[64:65], s[92:93], 0, v[128:129]
	s_mov_b32 m0, s94
	s_add_i32 s45, s81, 0xe000
	ds_read_b128 v[32:35], v149
	ds_read_b128 v[36:39], v149 offset:1024
	ds_read_b128 v[40:43], v149 offset:2048
	ds_read_b128 v[44:47], v149 offset:3072
	ds_read_b128 v[48:51], v149 offset:4096
	ds_read_b128 v[52:55], v149 offset:5120
	ds_read_b128 v[56:59], v149 offset:6144
	ds_read_b128 v[60:63], v149 offset:7168
	global_load_lds_dwordx4 v[64:65], off
	s_mov_b32 m0, s45
	v_lshl_add_u64 v[64:65], s[92:93], 0, v[132:133]
	global_load_lds_dwordx4 v[64:65], off
	s_waitcnt vmcnt(8)
	s_waitcnt lgkmcnt(0)
	s_barrier
	s_waitcnt lgkmcnt(0)
	v_mfma_f32_16x16x32_bf16 v[64:67], v[0:3], v[32:35], 0
	v_mfma_f32_16x16x32_bf16 v[68:71], v[8:11], v[32:35], 0
	v_mfma_f32_16x16x32_bf16 v[72:75], v[0:3], v[40:43], 0
	v_mfma_f32_16x16x32_bf16 v[76:79], v[8:11], v[40:43], 0
	v_mfma_f32_16x16x32_bf16 v[80:83], v[0:3], v[48:51], 0
	v_mfma_f32_16x16x32_bf16 v[84:87], v[8:11], v[48:51], 0
	v_mfma_f32_16x16x32_bf16 v[88:91], v[0:3], v[56:59], 0
	v_mfma_f32_16x16x32_bf16 v[92:95], v[8:11], v[56:59], 0
	v_mfma_f32_16x16x32_bf16 v[64:67], v[4:7], v[36:39], v[64:67]
	v_mfma_f32_16x16x32_bf16 v[68:71], v[12:15], v[36:39], v[68:71]
	v_mfma_f32_16x16x32_bf16 v[72:75], v[4:7], v[44:47], v[72:75]
	v_mfma_f32_16x16x32_bf16 v[76:79], v[12:15], v[44:47], v[76:79]
	v_mfma_f32_16x16x32_bf16 v[80:83], v[4:7], v[52:55], v[80:83]
	v_mfma_f32_16x16x32_bf16 v[84:87], v[12:15], v[52:55], v[84:87]
	v_mfma_f32_16x16x32_bf16 v[88:91], v[4:7], v[60:63], v[88:91]
	v_mfma_f32_16x16x32_bf16 v[92:95], v[12:15], v[60:63], v[92:95]
	v_mfma_f32_16x16x32_bf16 v[96:99], v[16:19], v[32:35], 0
	v_mfma_f32_16x16x32_bf16 v[32:35], v[24:27], v[32:35], 0
	v_mfma_f32_16x16x32_bf16 v[96:99], v[20:23], v[36:39], v[96:99]
	v_mfma_f32_16x16x32_bf16 v[32:35], v[28:31], v[36:39], v[32:35]
	v_mfma_f32_16x16x32_bf16 v[36:39], v[16:19], v[40:43], 0
	v_mfma_f32_16x16x32_bf16 v[40:43], v[24:27], v[40:43], 0
	v_mfma_f32_16x16x32_bf16 v[36:39], v[20:23], v[44:47], v[36:39]
	v_mfma_f32_16x16x32_bf16 v[40:43], v[28:31], v[44:47], v[40:43]
	v_mfma_f32_16x16x32_bf16 v[44:47], v[16:19], v[48:51], 0
	v_mfma_f32_16x16x32_bf16 v[48:51], v[24:27], v[48:51], 0
	v_mfma_f32_16x16x32_bf16 v[44:47], v[20:23], v[52:55], v[44:47]
	v_mfma_f32_16x16x32_bf16 v[48:51], v[28:31], v[52:55], v[48:51]
	v_mfma_f32_16x16x32_bf16 v[52:55], v[16:19], v[56:59], 0
	v_mfma_f32_16x16x32_bf16 v[56:59], v[24:27], v[56:59], 0
	v_mfma_f32_16x16x32_bf16 v[52:55], v[20:23], v[60:63], v[52:55]
	v_mfma_f32_16x16x32_bf16 v[56:59], v[28:31], v[60:63], v[56:59]
	s_barrier
	s_add_i32 s92, s88, s80
	v_lshl_add_u64 v[212:213], s[60:61], 0, v[130:131]
	s_add_i32 s49, s92, 0x2000
	v_lshl_add_u64 v[140:141], v[212:213], 0, s[38:39]
	s_mov_b32 m0, s92
	v_lshl_add_u64 v[214:215], s[60:61], 0, v[134:135]
	s_add_u32 s96, s60, 0x10100
	ds_read_b128 v[60:63], v149 offset:16384
	ds_read_b128 v[100:103], v149 offset:17408
	ds_read_b128 v[104:107], v149 offset:18432
	ds_read_b128 v[108:111], v149 offset:19456
	ds_read_b128 v[112:115], v149 offset:20480
	ds_read_b128 v[116:119], v149 offset:21504
	ds_read_b128 v[120:123], v149 offset:22528
	ds_read_b128 v[124:127], v149 offset:23552
	global_load_lds_dwordx4 v[140:141], off
	v_lshl_add_u64 v[140:141], v[214:215], 0, s[38:39]
	s_mov_b32 m0, s49
	s_addc_u32 s97, s61, 0
	s_add_i32 s55, s89, s80
	global_load_lds_dwordx4 v[140:141], off
	v_lshl_add_u64 v[140:141], s[96:97], 0, v[130:131]
	s_mov_b32 m0, s55
	s_add_i32 s57, s55, 0x2000
	global_load_lds_dwordx4 v[140:141], off
	v_lshl_add_u64 v[140:141], s[96:97], 0, v[134:135]
	s_mov_b32 m0, s57
	v_lshl_add_u64 v[216:217], s[58:59], 0, v[128:129]
	global_load_lds_dwordx4 v[140:141], off
	v_lshl_add_u64 v[140:141], v[216:217], 0, s[38:39]
	s_mov_b32 m0, s81
	v_lshl_add_u64 v[218:219], s[58:59], 0, v[132:133]
	global_load_lds_dwordx4 v[140:141], off
	s_mov_b32 m0, s82
	v_lshl_add_u64 v[140:141], v[218:219], 0, s[38:39]
	global_load_lds_dwordx4 v[140:141], off
	s_waitcnt vmcnt(8)
	s_waitcnt lgkmcnt(0)
	s_barrier
	s_waitcnt lgkmcnt(0)
	v_mfma_f32_16x16x32_bf16 v[140:143], v[0:3], v[60:63], 0
	v_mfma_f32_16x16x32_bf16 v[156:159], v[0:3], v[104:107], 0
	v_mfma_f32_16x16x32_bf16 v[164:167], v[0:3], v[112:115], 0
	v_mfma_f32_16x16x32_bf16 v[0:3], v[0:3], v[120:123], 0
	v_mfma_f32_16x16x32_bf16 v[140:143], v[4:7], v[100:103], v[140:143]
	v_mfma_f32_16x16x32_bf16 v[156:159], v[4:7], v[108:111], v[156:159]
	v_mfma_f32_16x16x32_bf16 v[164:167], v[4:7], v[116:119], v[164:167]
	v_mfma_f32_16x16x32_bf16 v[0:3], v[4:7], v[124:127], v[0:3]
	v_mfma_f32_16x16x32_bf16 v[4:7], v[8:11], v[120:123], 0
	v_mfma_f32_16x16x32_bf16 v[152:155], v[8:11], v[60:63], 0
	v_mfma_f32_16x16x32_bf16 v[160:163], v[8:11], v[104:107], 0
	v_mfma_f32_16x16x32_bf16 v[168:171], v[8:11], v[112:115], 0
	v_mfma_f32_16x16x32_bf16 v[4:7], v[12:15], v[124:127], v[4:7]
	v_mfma_f32_16x16x32_bf16 v[152:155], v[12:15], v[100:103], v[152:155]
	v_mfma_f32_16x16x32_bf16 v[160:163], v[12:15], v[108:111], v[160:163]
	v_mfma_f32_16x16x32_bf16 v[168:171], v[12:15], v[116:119], v[168:171]
	v_mfma_f32_16x16x32_bf16 v[8:11], v[16:19], v[60:63], 0
	v_mfma_f32_16x16x32_bf16 v[12:15], v[24:27], v[60:63], 0
	v_mfma_f32_16x16x32_bf16 v[8:11], v[20:23], v[100:103], v[8:11]
	v_mfma_f32_16x16x32_bf16 v[12:15], v[28:31], v[100:103], v[12:15]
	v_mfma_f32_16x16x32_bf16 v[60:63], v[16:19], v[104:107], 0
	v_mfma_f32_16x16x32_bf16 v[100:103], v[24:27], v[104:107], 0
	v_mfma_f32_16x16x32_bf16 v[104:107], v[16:19], v[112:115], 0
	v_mfma_f32_16x16x32_bf16 v[16:19], v[16:19], v[120:123], 0
	v_mfma_f32_16x16x32_bf16 v[60:63], v[20:23], v[108:111], v[60:63]
	v_mfma_f32_16x16x32_bf16 v[100:103], v[28:31], v[108:111], v[100:103]
	v_mfma_f32_16x16x32_bf16 v[104:107], v[20:23], v[116:119], v[104:107]
	v_mfma_f32_16x16x32_bf16 v[108:111], v[24:27], v[112:115], 0
	v_mfma_f32_16x16x32_bf16 v[16:19], v[20:23], v[124:127], v[16:19]
	v_mfma_f32_16x16x32_bf16 v[20:23], v[24:27], v[120:123], 0
	v_mfma_f32_16x16x32_bf16 v[108:111], v[28:31], v[116:119], v[108:111]
	v_mfma_f32_16x16x32_bf16 v[20:23], v[28:31], v[124:127], v[20:23]
	s_barrier
	s_add_i32 s95, 0, 0x18000
	s_add_i32 vcc_lo, 0, 0x1c000
	v_add_u32_e32 v151, s95, v145
	v_add_u32_e32 v224, vcc_lo, v145
	ds_read_b128 v[24:27], v151
	ds_read_b128 v[28:31], v151 offset:1024
	ds_read_b128 v[112:115], v151 offset:2048
	ds_read_b128 v[116:119], v151 offset:3072
	ds_read_b128 v[120:123], v224
	ds_read_b128 v[124:127], v224 offset:1024
	ds_read_b128 v[172:175], v224 offset:2048
	ds_read_b128 v[176:179], v224 offset:3072
	s_add_u32 s96, s58, 0x10100
	s_addc_u32 s97, s59, 0
	s_mov_b32 m0, s83
	v_lshl_add_u64 v[220:221], s[96:97], 0, v[128:129]
	ds_read_b128 v[180:183], v149 offset:32768
	ds_read_b128 v[184:187], v149 offset:33792
	ds_read_b128 v[188:191], v149 offset:34816
	ds_read_b128 v[192:195], v149 offset:35840
	ds_read_b128 v[196:199], v149 offset:36864
	ds_read_b128 v[200:203], v149 offset:37888
	ds_read_b128 v[204:207], v149 offset:38912
	ds_read_b128 v[208:211], v149 offset:39936
	global_load_lds_dwordx4 v[220:221], off
	s_mov_b32 m0, s84
	v_lshl_add_u64 v[220:221], s[96:97], 0, v[132:133]
	global_load_lds_dwordx4 v[220:221], off
	s_waitcnt vmcnt(8)
	s_waitcnt lgkmcnt(0)
	s_barrier
	s_waitcnt lgkmcnt(0)
	v_mfma_f32_16x16x32_bf16 v[64:67], v[24:27], v[180:183], v[64:67]
	v_mfma_f32_16x16x32_bf16 v[68:71], v[112:115], v[180:183], v[68:71]
	v_mfma_f32_16x16x32_bf16 v[72:75], v[24:27], v[188:191], v[72:75]
	v_mfma_f32_16x16x32_bf16 v[76:79], v[112:115], v[188:191], v[76:79]
	v_mfma_f32_16x16x32_bf16 v[80:83], v[24:27], v[196:199], v[80:83]
	v_mfma_f32_16x16x32_bf16 v[84:87], v[112:115], v[196:199], v[84:87]
	v_mfma_f32_16x16x32_bf16 v[88:91], v[24:27], v[204:207], v[88:91]
	v_mfma_f32_16x16x32_bf16 v[92:95], v[112:115], v[204:207], v[92:95]
	v_mfma_f32_16x16x32_bf16 v[64:67], v[28:31], v[184:187], v[64:67]
	v_mfma_f32_16x16x32_bf16 v[68:71], v[116:119], v[184:187], v[68:71]
	v_mfma_f32_16x16x32_bf16 v[72:75], v[28:31], v[192:195], v[72:75]
	v_mfma_f32_16x16x32_bf16 v[76:79], v[116:119], v[192:195], v[76:79]
	v_mfma_f32_16x16x32_bf16 v[80:83], v[28:31], v[200:203], v[80:83]
	v_mfma_f32_16x16x32_bf16 v[84:87], v[116:119], v[200:203], v[84:87]
	v_mfma_f32_16x16x32_bf16 v[88:91], v[28:31], v[208:211], v[88:91]
	v_mfma_f32_16x16x32_bf16 v[92:95], v[116:119], v[208:211], v[92:95]
	v_mfma_f32_16x16x32_bf16 v[96:99], v[120:123], v[180:183], v[96:99]
	v_mfma_f32_16x16x32_bf16 v[32:35], v[172:175], v[180:183], v[32:35]
	v_mfma_f32_16x16x32_bf16 v[36:39], v[120:123], v[188:191], v[36:39]
	v_mfma_f32_16x16x32_bf16 v[40:43], v[172:175], v[188:191], v[40:43]
	v_mfma_f32_16x16x32_bf16 v[44:47], v[120:123], v[196:199], v[44:47]
	v_mfma_f32_16x16x32_bf16 v[48:51], v[172:175], v[196:199], v[48:51]
	v_mfma_f32_16x16x32_bf16 v[52:55], v[120:123], v[204:207], v[52:55]
	v_mfma_f32_16x16x32_bf16 v[56:59], v[172:175], v[204:207], v[56:59]
	v_mfma_f32_16x16x32_bf16 v[96:99], v[124:127], v[184:187], v[96:99]
	v_mfma_f32_16x16x32_bf16 v[32:35], v[176:179], v[184:187], v[32:35]
	v_mfma_f32_16x16x32_bf16 v[36:39], v[124:127], v[192:195], v[36:39]
	v_mfma_f32_16x16x32_bf16 v[40:43], v[176:179], v[192:195], v[40:43]
	v_mfma_f32_16x16x32_bf16 v[44:47], v[124:127], v[200:203], v[44:47]
	v_mfma_f32_16x16x32_bf16 v[48:51], v[176:179], v[200:203], v[48:51]
	v_mfma_f32_16x16x32_bf16 v[52:55], v[124:127], v[208:211], v[52:55]
	v_mfma_f32_16x16x32_bf16 v[56:59], v[176:179], v[208:211], v[56:59]
	s_barrier
	s_add_i32 s95, s95, s80
	s_add_i32 s93, s95, 0x2000
	v_lshl_add_u64 v[212:213], v[212:213], 0, s[40:41]
	s_mov_b32 m0, s95
	s_add_u32 s96, s60, 0x10180
	ds_read_b128 v[180:183], v149 offset:49152
	ds_read_b128 v[184:187], v149 offset:50176
	ds_read_b128 v[188:191], v149 offset:51200
	ds_read_b128 v[192:195], v149 offset:52224
	ds_read_b128 v[196:199], v149 offset:53248
	ds_read_b128 v[200:203], v149 offset:54272
	ds_read_b128 v[204:207], v149 offset:55296
	ds_read_b128 v[208:211], v149 offset:56320
	global_load_lds_dwordx4 v[212:213], off
	v_lshl_add_u64 v[212:213], v[214:215], 0, s[40:41]
	s_mov_b32 m0, s93
	s_addc_u32 s97, s61, 0
	s_add_i32 s60, vcc_lo, s80
	global_load_lds_dwordx4 v[212:213], off
	v_lshl_add_u64 v[212:213], s[96:97], 0, v[130:131]
	s_mov_b32 m0, s60
	s_add_i32 s61, s60, 0x2000
	global_load_lds_dwordx4 v[212:213], off
	s_mov_b32 m0, s61
	v_lshl_add_u64 v[212:213], s[96:97], 0, v[134:135]
	global_load_lds_dwordx4 v[212:213], off
	s_mov_b32 m0, s86
	v_lshl_add_u64 v[212:213], v[216:217], 0, s[40:41]
	global_load_lds_dwordx4 v[212:213], off
	s_mov_b32 m0, s87
	v_lshl_add_u64 v[212:213], v[218:219], 0, s[40:41]
	global_load_lds_dwordx4 v[212:213], off
	s_waitcnt vmcnt(8)
	s_waitcnt lgkmcnt(0)
	s_barrier
	s_waitcnt lgkmcnt(0)
	v_mfma_f32_16x16x32_bf16 v[0:3], v[24:27], v[204:207], v[0:3]
	v_mfma_f32_16x16x32_bf16 v[4:7], v[112:115], v[204:207], v[4:7]
	v_mfma_f32_16x16x32_bf16 v[140:143], v[24:27], v[180:183], v[140:143]
	v_mfma_f32_16x16x32_bf16 v[152:155], v[112:115], v[180:183], v[152:155]
	v_mfma_f32_16x16x32_bf16 v[156:159], v[24:27], v[188:191], v[156:159]
	v_mfma_f32_16x16x32_bf16 v[160:163], v[112:115], v[188:191], v[160:163]
	v_mfma_f32_16x16x32_bf16 v[164:167], v[24:27], v[196:199], v[164:167]
	v_mfma_f32_16x16x32_bf16 v[168:171], v[112:115], v[196:199], v[168:171]
	v_mfma_f32_16x16x32_bf16 v[0:3], v[28:31], v[208:211], v[0:3]
	v_mfma_f32_16x16x32_bf16 v[4:7], v[116:119], v[208:211], v[4:7]
	v_mfma_f32_16x16x32_bf16 v[140:143], v[28:31], v[184:187], v[140:143]
	v_mfma_f32_16x16x32_bf16 v[152:155], v[116:119], v[184:187], v[152:155]
	v_mfma_f32_16x16x32_bf16 v[156:159], v[28:31], v[192:195], v[156:159]
	v_mfma_f32_16x16x32_bf16 v[160:163], v[116:119], v[192:195], v[160:163]
	v_mfma_f32_16x16x32_bf16 v[164:167], v[28:31], v[200:203], v[164:167]
	v_mfma_f32_16x16x32_bf16 v[168:171], v[116:119], v[200:203], v[168:171]
	v_mfma_f32_16x16x32_bf16 v[8:11], v[120:123], v[180:183], v[8:11]
	v_mfma_f32_16x16x32_bf16 v[12:15], v[172:175], v[180:183], v[12:15]
	v_mfma_f32_16x16x32_bf16 v[24:27], v[120:123], v[188:191], v[60:63]
	v_mfma_f32_16x16x32_bf16 v[28:31], v[172:175], v[188:191], v[100:103]
	v_mfma_f32_16x16x32_bf16 v[60:63], v[120:123], v[196:199], v[104:107]
	v_mfma_f32_16x16x32_bf16 v[100:103], v[172:175], v[196:199], v[108:111]
	v_mfma_f32_16x16x32_bf16 v[16:19], v[120:123], v[204:207], v[16:19]
	v_mfma_f32_16x16x32_bf16 v[20:23], v[172:175], v[204:207], v[20:23]
	v_mfma_f32_16x16x32_bf16 v[8:11], v[124:127], v[184:187], v[8:11]
	v_mfma_f32_16x16x32_bf16 v[12:15], v[176:179], v[184:187], v[12:15]
	v_mfma_f32_16x16x32_bf16 v[24:27], v[124:127], v[192:195], v[24:27]
	v_mfma_f32_16x16x32_bf16 v[28:31], v[176:179], v[192:195], v[28:31]
	v_mfma_f32_16x16x32_bf16 v[60:63], v[124:127], v[200:203], v[60:63]
	v_mfma_f32_16x16x32_bf16 v[100:103], v[176:179], v[200:203], v[100:103]
	v_mfma_f32_16x16x32_bf16 v[16:19], v[124:127], v[208:211], v[16:19]
	v_mfma_f32_16x16x32_bf16 v[20:23], v[176:179], v[208:211], v[20:23]
	s_barrier
	ds_read_b128 v[104:107], v147
	ds_read_b128 v[108:111], v147 offset:1024
	ds_read_b128 v[112:115], v147 offset:2048
	ds_read_b128 v[116:119], v147 offset:3072
	ds_read_b128 v[120:123], v148
	ds_read_b128 v[124:127], v148 offset:1024
	ds_read_b128 v[172:175], v148 offset:2048
	ds_read_b128 v[176:179], v148 offset:3072
	s_add_u32 s58, s58, 0x10180
	s_addc_u32 s59, s59, 0
	s_mov_b32 m0, s94
	v_lshl_add_u64 v[212:213], s[58:59], 0, v[128:129]
	ds_read_b128 v[180:183], v149
	ds_read_b128 v[184:187], v149 offset:1024
	ds_read_b128 v[188:191], v149 offset:2048
	ds_read_b128 v[192:195], v149 offset:3072
	ds_read_b128 v[196:199], v149 offset:4096
	ds_read_b128 v[200:203], v149 offset:5120
	ds_read_b128 v[204:207], v149 offset:6144
	ds_read_b128 v[208:211], v149 offset:7168
	global_load_lds_dwordx4 v[212:213], off
	s_mov_b32 m0, s45
	v_lshl_add_u64 v[212:213], s[58:59], 0, v[132:133]
	global_load_lds_dwordx4 v[212:213], off
	s_waitcnt vmcnt(8)
	s_waitcnt lgkmcnt(0)
	s_barrier
	s_waitcnt lgkmcnt(0)
	v_mfma_f32_16x16x32_bf16 v[64:67], v[104:107], v[180:183], v[64:67]
	v_mfma_f32_16x16x32_bf16 v[68:71], v[112:115], v[180:183], v[68:71]
	v_mfma_f32_16x16x32_bf16 v[72:75], v[104:107], v[188:191], v[72:75]
	v_mfma_f32_16x16x32_bf16 v[76:79], v[112:115], v[188:191], v[76:79]
	v_mfma_f32_16x16x32_bf16 v[80:83], v[104:107], v[196:199], v[80:83]
	v_mfma_f32_16x16x32_bf16 v[84:87], v[112:115], v[196:199], v[84:87]
	v_mfma_f32_16x16x32_bf16 v[88:91], v[104:107], v[204:207], v[88:91]
	v_mfma_f32_16x16x32_bf16 v[64:67], v[108:111], v[184:187], v[64:67]
	v_mfma_f32_16x16x32_bf16 v[68:71], v[116:119], v[184:187], v[68:71]
	v_mfma_f32_16x16x32_bf16 v[72:75], v[108:111], v[192:195], v[72:75]
	v_mfma_f32_16x16x32_bf16 v[76:79], v[116:119], v[192:195], v[76:79]
	v_mfma_f32_16x16x32_bf16 v[80:83], v[108:111], v[200:203], v[80:83]
	v_mfma_f32_16x16x32_bf16 v[84:87], v[116:119], v[200:203], v[84:87]
	v_mfma_f32_16x16x32_bf16 v[212:215], v[108:111], v[208:211], v[88:91]
	v_mfma_f32_16x16x32_bf16 v[88:91], v[112:115], v[204:207], v[92:95]
	v_mfma_f32_16x16x32_bf16 v[216:219], v[116:119], v[208:211], v[88:91]
	v_mfma_f32_16x16x32_bf16 v[88:91], v[120:123], v[180:183], v[96:99]
	v_mfma_f32_16x16x32_bf16 v[32:35], v[172:175], v[180:183], v[32:35]
	v_mfma_f32_16x16x32_bf16 v[36:39], v[120:123], v[188:191], v[36:39]
	v_mfma_f32_16x16x32_bf16 v[40:43], v[172:175], v[188:191], v[40:43]
	v_mfma_f32_16x16x32_bf16 v[44:47], v[120:123], v[196:199], v[44:47]
	v_mfma_f32_16x16x32_bf16 v[48:51], v[172:175], v[196:199], v[48:51]
	v_mfma_f32_16x16x32_bf16 v[52:55], v[120:123], v[204:207], v[52:55]
	v_mfma_f32_16x16x32_bf16 v[56:59], v[172:175], v[204:207], v[56:59]
	v_mfma_f32_16x16x32_bf16 v[96:99], v[124:127], v[184:187], v[88:91]
	v_mfma_f32_16x16x32_bf16 v[32:35], v[176:179], v[184:187], v[32:35]
	v_mfma_f32_16x16x32_bf16 v[36:39], v[124:127], v[192:195], v[36:39]
	v_mfma_f32_16x16x32_bf16 v[40:43], v[176:179], v[192:195], v[40:43]
	v_mfma_f32_16x16x32_bf16 v[44:47], v[124:127], v[200:203], v[44:47]
	v_mfma_f32_16x16x32_bf16 v[48:51], v[176:179], v[200:203], v[48:51]
	v_mfma_f32_16x16x32_bf16 v[52:55], v[124:127], v[208:211], v[52:55]
	v_mfma_f32_16x16x32_bf16 v[56:59], v[176:179], v[208:211], v[56:59]
	s_barrier
	s_mov_b32 m0, s92
	v_lshl_add_u64 v[244:245], s[62:63], 0, v[130:131]
	s_add_u32 s58, s62, 0x10000
	ds_read_b128 v[88:91], v149 offset:16384
	ds_read_b128 v[92:95], v149 offset:17408
	ds_read_b128 v[180:183], v149 offset:18432
	ds_read_b128 v[184:187], v149 offset:19456
	ds_read_b128 v[188:191], v149 offset:20480
	ds_read_b128 v[192:195], v149 offset:21504
	ds_read_b128 v[196:199], v149 offset:22528
	ds_read_b128 v[200:203], v149 offset:23552
	global_load_lds_dwordx4 v[244:245], off
	v_lshl_add_u64 v[246:247], s[62:63], 0, v[134:135]
	s_mov_b32 m0, s49
	s_addc_u32 s59, s63, 0
	global_load_lds_dwordx4 v[246:247], off
	v_lshl_add_u64 v[204:205], s[58:59], 0, v[130:131]
	s_mov_b32 m0, s55
	v_lshl_add_u64 v[248:249], s[64:65], 0, v[128:129]
	global_load_lds_dwordx4 v[204:205], off
	v_lshl_add_u64 v[204:205], s[58:59], 0, v[134:135]
	s_mov_b32 m0, s57
	v_lshl_add_u64 v[250:251], s[64:65], 0, v[132:133]
	global_load_lds_dwordx4 v[204:205], off
	s_mov_b32 m0, s81
	s_nop 0
	global_load_lds_dwordx4 v[248:249], off
	s_mov_b32 m0, s82
	s_nop 0
	global_load_lds_dwordx4 v[250:251], off
	s_waitcnt vmcnt(8)
	s_waitcnt lgkmcnt(0)
	s_barrier
	s_waitcnt lgkmcnt(0)
	v_mfma_f32_16x16x32_bf16 v[0:3], v[104:107], v[196:199], v[0:3]
	v_mfma_f32_16x16x32_bf16 v[4:7], v[112:115], v[196:199], v[4:7]
	v_mfma_f32_16x16x32_bf16 v[140:143], v[104:107], v[88:91], v[140:143]
	v_mfma_f32_16x16x32_bf16 v[152:155], v[112:115], v[88:91], v[152:155]
	v_mfma_f32_16x16x32_bf16 v[156:159], v[104:107], v[180:183], v[156:159]
	v_mfma_f32_16x16x32_bf16 v[160:163], v[112:115], v[180:183], v[160:163]
	v_mfma_f32_16x16x32_bf16 v[164:167], v[104:107], v[188:191], v[164:167]
	v_mfma_f32_16x16x32_bf16 v[168:171], v[112:115], v[188:191], v[168:171]
	v_mfma_f32_16x16x32_bf16 v[0:3], v[108:111], v[200:203], v[0:3]
	v_mfma_f32_16x16x32_bf16 v[4:7], v[116:119], v[200:203], v[4:7]
	v_mfma_f32_16x16x32_bf16 v[140:143], v[108:111], v[92:95], v[140:143]
	v_mfma_f32_16x16x32_bf16 v[152:155], v[116:119], v[92:95], v[152:155]
	v_mfma_f32_16x16x32_bf16 v[156:159], v[108:111], v[184:187], v[156:159]
	v_mfma_f32_16x16x32_bf16 v[160:163], v[116:119], v[184:187], v[160:163]
	v_mfma_f32_16x16x32_bf16 v[164:167], v[108:111], v[192:195], v[164:167]
	v_mfma_f32_16x16x32_bf16 v[168:171], v[116:119], v[192:195], v[168:171]
	v_mfma_f32_16x16x32_bf16 v[8:11], v[120:123], v[88:91], v[8:11]
	v_mfma_f32_16x16x32_bf16 v[204:207], v[124:127], v[92:95], v[8:11]
	v_mfma_f32_16x16x32_bf16 v[8:11], v[172:175], v[88:91], v[12:15]
	v_mfma_f32_16x16x32_bf16 v[208:211], v[176:179], v[92:95], v[8:11]
	v_mfma_f32_16x16x32_bf16 v[8:11], v[120:123], v[180:183], v[24:27]
	v_mfma_f32_16x16x32_bf16 v[220:223], v[124:127], v[184:187], v[8:11]
	v_mfma_f32_16x16x32_bf16 v[8:11], v[172:175], v[180:183], v[28:31]
	v_mfma_f32_16x16x32_bf16 v[180:183], v[176:179], v[184:187], v[8:11]
	v_mfma_f32_16x16x32_bf16 v[8:11], v[120:123], v[188:191], v[60:63]
	v_mfma_f32_16x16x32_bf16 v[184:187], v[124:127], v[192:195], v[8:11]
	v_mfma_f32_16x16x32_bf16 v[8:11], v[172:175], v[188:191], v[100:103]
	v_mfma_f32_16x16x32_bf16 v[188:191], v[176:179], v[192:195], v[8:11]
	v_mfma_f32_16x16x32_bf16 v[8:11], v[120:123], v[196:199], v[16:19]
	v_mfma_f32_16x16x32_bf16 v[192:195], v[124:127], v[200:203], v[8:11]
	v_mfma_f32_16x16x32_bf16 v[8:11], v[172:175], v[196:199], v[20:23]
	v_mfma_f32_16x16x32_bf16 v[172:175], v[176:179], v[200:203], v[8:11]
	s_barrier
	s_nop 4
	ds_read_b128 v[8:11], v151
	ds_read_b128 v[12:15], v151 offset:1024
	ds_read_b128 v[16:19], v151 offset:2048
	ds_read_b128 v[20:23], v151 offset:3072
	ds_read_b128 v[176:179], v224
	ds_read_b128 v[196:199], v224 offset:1024
	ds_read_b128 v[200:203], v224 offset:2048
	ds_read_b128 v[224:227], v224 offset:3072
	s_add_u32 s58, s64, 0x10000
	s_addc_u32 s59, s65, 0
	s_mov_b32 m0, s83
	v_lshl_add_u64 v[88:89], s[58:59], 0, v[128:129]
	ds_read_b128 v[24:27], v149 offset:32768
	ds_read_b128 v[28:31], v149 offset:33792
	ds_read_b128 v[60:63], v149 offset:34816
	ds_read_b128 v[100:103], v149 offset:35840
	ds_read_b128 v[228:231], v149 offset:36864
	ds_read_b128 v[232:235], v149 offset:37888
	ds_read_b128 v[236:239], v149 offset:38912
	ds_read_b128 v[240:243], v149 offset:39936
	global_load_lds_dwordx4 v[88:89], off
	s_mov_b32 m0, s84
	v_lshl_add_u64 v[88:89], s[58:59], 0, v[132:133]
	global_load_lds_dwordx4 v[88:89], off
	s_waitcnt vmcnt(8)
	s_waitcnt lgkmcnt(0)
	s_barrier
	s_waitcnt lgkmcnt(0)
	v_mfma_f32_16x16x32_bf16 v[64:67], v[8:11], v[24:27], v[64:67]
	v_mfma_f32_16x16x32_bf16 v[120:123], v[12:15], v[28:31], v[64:67]
	v_mfma_f32_16x16x32_bf16 v[64:67], v[16:19], v[24:27], v[68:71]
	v_mfma_f32_16x16x32_bf16 v[124:127], v[20:23], v[28:31], v[64:67]
	v_mfma_f32_16x16x32_bf16 v[64:67], v[8:11], v[60:63], v[72:75]
	v_mfma_f32_16x16x32_bf16 v[104:107], v[12:15], v[100:103], v[64:67]
	v_mfma_f32_16x16x32_bf16 v[64:67], v[16:19], v[60:63], v[76:79]
	v_mfma_f32_16x16x32_bf16 v[108:111], v[20:23], v[100:103], v[64:67]
	v_mfma_f32_16x16x32_bf16 v[64:67], v[8:11], v[228:231], v[80:83]
	v_mfma_f32_16x16x32_bf16 v[88:91], v[12:15], v[232:235], v[64:67]
	v_mfma_f32_16x16x32_bf16 v[64:67], v[16:19], v[228:231], v[84:87]
	v_mfma_f32_16x16x32_bf16 v[92:95], v[20:23], v[232:235], v[64:67]
	v_mfma_f32_16x16x32_bf16 v[64:67], v[8:11], v[236:239], v[212:215]
	v_mfma_f32_16x16x32_bf16 v[72:75], v[12:15], v[240:243], v[64:67]
	v_mfma_f32_16x16x32_bf16 v[64:67], v[16:19], v[236:239], v[216:219]
	v_mfma_f32_16x16x32_bf16 v[76:79], v[20:23], v[240:243], v[64:67]
	v_mfma_f32_16x16x32_bf16 v[64:67], v[176:179], v[24:27], v[96:99]
	v_mfma_f32_16x16x32_bf16 v[24:27], v[200:203], v[24:27], v[32:35]
	v_mfma_f32_16x16x32_bf16 v[116:119], v[224:227], v[28:31], v[24:27]
	v_mfma_f32_16x16x32_bf16 v[24:27], v[176:179], v[60:63], v[36:39]
	v_mfma_f32_16x16x32_bf16 v[96:99], v[196:199], v[100:103], v[24:27]
	v_mfma_f32_16x16x32_bf16 v[24:27], v[200:203], v[60:63], v[40:43]
	v_mfma_f32_16x16x32_bf16 v[100:103], v[224:227], v[100:103], v[24:27]
	v_mfma_f32_16x16x32_bf16 v[24:27], v[176:179], v[228:231], v[44:47]
	v_mfma_f32_16x16x32_bf16 v[80:83], v[196:199], v[232:235], v[24:27]
	v_mfma_f32_16x16x32_bf16 v[24:27], v[200:203], v[228:231], v[48:51]
	v_mfma_f32_16x16x32_bf16 v[84:87], v[224:227], v[232:235], v[24:27]
	v_mfma_f32_16x16x32_bf16 v[24:27], v[176:179], v[236:239], v[52:55]
	v_mfma_f32_16x16x32_bf16 v[112:115], v[196:199], v[28:31], v[64:67]
	v_mfma_f32_16x16x32_bf16 v[64:67], v[196:199], v[240:243], v[24:27]
	v_mfma_f32_16x16x32_bf16 v[24:27], v[200:203], v[236:239], v[56:59]
	v_mfma_f32_16x16x32_bf16 v[68:71], v[224:227], v[240:243], v[24:27]
	s_barrier
	s_mov_b32 m0, s95
	s_nop 3
	v_lshl_add_u64 v[24:25], v[244:245], 0, s[18:19]
	s_add_u32 s58, s62, 0x10080
	ds_read_b128 v[32:35], v149 offset:49152
	ds_read_b128 v[36:39], v149 offset:50176
	ds_read_b128 v[212:215], v149 offset:51200
	ds_read_b128 v[216:219], v149 offset:52224
	ds_read_b128 v[228:231], v149 offset:53248
	ds_read_b128 v[232:235], v149 offset:54272
	ds_read_b128 v[236:239], v149 offset:55296
	ds_read_b128 v[240:243], v149 offset:56320
	global_load_lds_dwordx4 v[24:25], off
	v_lshl_add_u64 v[24:25], v[246:247], 0, s[18:19]
	s_mov_b32 m0, s93
	s_addc_u32 s59, s63, 0
	global_load_lds_dwordx4 v[24:25], off
	s_mov_b32 m0, s60
	v_lshl_add_u64 v[24:25], s[58:59], 0, v[130:131]
	global_load_lds_dwordx4 v[24:25], off
	s_mov_b32 m0, s61
	v_lshl_add_u64 v[24:25], s[58:59], 0, v[134:135]
	global_load_lds_dwordx4 v[24:25], off
	s_mov_b32 m0, s86
	v_lshl_add_u64 v[24:25], v[248:249], 0, s[18:19]
	global_load_lds_dwordx4 v[24:25], off
	s_mov_b32 m0, s87
	v_lshl_add_u64 v[24:25], v[250:251], 0, s[18:19]
	global_load_lds_dwordx4 v[24:25], off
	s_waitcnt vmcnt(8)
	s_waitcnt lgkmcnt(0)
	s_barrier
	s_waitcnt lgkmcnt(0)
	v_mfma_f32_16x16x32_bf16 v[24:27], v[8:11], v[32:35], v[140:143]
	v_mfma_f32_16x16x32_bf16 v[56:59], v[12:15], v[36:39], v[24:27]
	v_mfma_f32_16x16x32_bf16 v[24:27], v[16:19], v[32:35], v[152:155]
	v_mfma_f32_16x16x32_bf16 v[60:63], v[20:23], v[36:39], v[24:27]
	v_mfma_f32_16x16x32_bf16 v[24:27], v[8:11], v[212:215], v[156:159]
	v_mfma_f32_16x16x32_bf16 v[40:43], v[12:15], v[216:219], v[24:27]
	v_mfma_f32_16x16x32_bf16 v[24:27], v[16:19], v[212:215], v[160:163]
	v_mfma_f32_16x16x32_bf16 v[0:3], v[8:11], v[236:239], v[0:3]
	v_mfma_f32_16x16x32_bf16 v[44:47], v[20:23], v[216:219], v[24:27]
	v_mfma_f32_16x16x32_bf16 v[24:27], v[8:11], v[228:231], v[164:167]
	v_mfma_f32_16x16x32_bf16 v[28:31], v[16:19], v[228:231], v[168:171]
	v_mfma_f32_16x16x32_bf16 v[8:11], v[12:15], v[240:243], v[0:3]
	v_mfma_f32_16x16x32_bf16 v[0:3], v[16:19], v[236:239], v[4:7]
	v_mfma_f32_16x16x32_bf16 v[24:27], v[12:15], v[232:235], v[24:27]
	v_mfma_f32_16x16x32_bf16 v[28:31], v[20:23], v[232:235], v[28:31]
	v_mfma_f32_16x16x32_bf16 v[12:15], v[20:23], v[240:243], v[0:3]
	v_mfma_f32_16x16x32_bf16 v[0:3], v[176:179], v[32:35], v[204:207]
	v_mfma_f32_16x16x32_bf16 v[48:51], v[196:199], v[36:39], v[0:3]
	v_mfma_f32_16x16x32_bf16 v[0:3], v[200:203], v[32:35], v[208:211]
	v_mfma_f32_16x16x32_bf16 v[52:55], v[224:227], v[36:39], v[0:3]
	v_mfma_f32_16x16x32_bf16 v[0:3], v[176:179], v[212:215], v[220:223]
	v_mfma_f32_16x16x32_bf16 v[32:35], v[196:199], v[216:219], v[0:3]
	v_mfma_f32_16x16x32_bf16 v[0:3], v[200:203], v[212:215], v[180:183]
	v_mfma_f32_16x16x32_bf16 v[36:39], v[224:227], v[216:219], v[0:3]
	v_mfma_f32_16x16x32_bf16 v[0:3], v[176:179], v[228:231], v[184:187]
	v_mfma_f32_16x16x32_bf16 v[16:19], v[196:199], v[232:235], v[0:3]
	v_mfma_f32_16x16x32_bf16 v[0:3], v[200:203], v[228:231], v[188:191]
	v_mfma_f32_16x16x32_bf16 v[20:23], v[224:227], v[232:235], v[0:3]
	v_mfma_f32_16x16x32_bf16 v[0:3], v[176:179], v[236:239], v[192:195]
	v_mfma_f32_16x16x32_bf16 v[4:7], v[200:203], v[236:239], v[172:175]
	v_mfma_f32_16x16x32_bf16 v[0:3], v[196:199], v[240:243], v[0:3]
	v_mfma_f32_16x16x32_bf16 v[4:7], v[224:227], v[240:243], v[4:7]
	s_barrier
	s_andn2_b64 vcc, exec, s[24:25]
	s_cbranch_vccnz .LBB0_499
	s_barrier

.LBB0_546:
	v_add_u32_e32 v1, s80, v155
	ds_read_b128 v[146:149], v1
	ds_read_b128 v[150:153], v1 offset:1024
	ds_read_b128 v[162:165], v1 offset:2048
	ds_read_b128 v[166:169], v1 offset:3072
	v_add_u32_e32 v1, s81, v155
	ds_read_b128 v[170:173], v1
	ds_read_b128 v[174:177], v1 offset:1024
	ds_read_b128 v[178:181], v1 offset:2048
	ds_read_b128 v[182:185], v1 offset:3072
	s_and_b64 s[56:57], exec, s[56:57]
	s_cselect_b32 s57, s43, s91
	s_cselect_b32 s56, s89, s90
	s_add_u32 s96, s93, 0x40000
	s_addc_u32 s97, s94, 0
	v_lshl_add_u64 v[2:3], s[96:97], 0, v[132:133]
	s_add_i32 m0, s9, 0xc000
	ds_read_b128 v[186:189], v159
	ds_read_b128 v[190:193], v159 offset:1024
	ds_read_b128 v[194:197], v159 offset:2048
	ds_read_b128 v[198:201], v159 offset:3072
	ds_read_b128 v[202:205], v159 offset:4096
	ds_read_b128 v[206:209], v159 offset:5120
	ds_read_b128 v[210:213], v159 offset:6144
	ds_read_b128 v[214:217], v159 offset:7168
	global_load_lds_dwordx4 v[2:3], off
	s_add_i32 m0, s9, 0xe000
	v_lshl_add_u64 v[2:3], s[96:97], 0, v[136:137]
	global_load_lds_dwordx4 v[2:3], off
	s_waitcnt vmcnt(8)
	s_waitcnt lgkmcnt(0)
	s_barrier
	s_waitcnt lgkmcnt(0)
	v_mfma_f32_16x16x32_bf16 v[128:131], v[146:149], v[186:189], v[128:131]
	v_mfma_f32_16x16x32_bf16 v[124:127], v[162:165], v[186:189], v[124:127]
	v_mfma_f32_16x16x32_bf16 v[112:115], v[146:149], v[194:197], v[112:115]
	v_mfma_f32_16x16x32_bf16 v[108:111], v[162:165], v[194:197], v[108:111]
	v_mfma_f32_16x16x32_bf16 v[96:99], v[146:149], v[202:205], v[96:99]
	v_mfma_f32_16x16x32_bf16 v[92:95], v[162:165], v[202:205], v[92:95]
	v_mfma_f32_16x16x32_bf16 v[80:83], v[146:149], v[210:213], v[80:83]
	v_mfma_f32_16x16x32_bf16 v[76:79], v[162:165], v[210:213], v[76:79]
	v_mfma_f32_16x16x32_bf16 v[128:131], v[150:153], v[190:193], v[128:131]
	v_mfma_f32_16x16x32_bf16 v[124:127], v[166:169], v[190:193], v[124:127]
	v_mfma_f32_16x16x32_bf16 v[112:115], v[150:153], v[198:201], v[112:115]
	v_mfma_f32_16x16x32_bf16 v[108:111], v[166:169], v[198:201], v[108:111]
	v_mfma_f32_16x16x32_bf16 v[96:99], v[150:153], v[206:209], v[96:99]
	v_mfma_f32_16x16x32_bf16 v[92:95], v[166:169], v[206:209], v[92:95]
	v_mfma_f32_16x16x32_bf16 v[80:83], v[150:153], v[214:217], v[80:83]
	v_mfma_f32_16x16x32_bf16 v[76:79], v[166:169], v[214:217], v[76:79]
	v_mfma_f32_16x16x32_bf16 v[120:123], v[170:173], v[186:189], v[120:123]
	v_mfma_f32_16x16x32_bf16 v[116:119], v[178:181], v[186:189], v[116:119]
	v_mfma_f32_16x16x32_bf16 v[104:107], v[170:173], v[194:197], v[104:107]
	v_mfma_f32_16x16x32_bf16 v[100:103], v[178:181], v[194:197], v[100:103]
	v_mfma_f32_16x16x32_bf16 v[88:91], v[170:173], v[202:205], v[88:91]
	v_mfma_f32_16x16x32_bf16 v[84:87], v[178:181], v[202:205], v[84:87]
	v_mfma_f32_16x16x32_bf16 v[72:75], v[170:173], v[210:213], v[72:75]
	v_mfma_f32_16x16x32_bf16 v[68:71], v[178:181], v[210:213], v[68:71]
	v_mfma_f32_16x16x32_bf16 v[120:123], v[174:177], v[190:193], v[120:123]
	v_mfma_f32_16x16x32_bf16 v[116:119], v[182:185], v[190:193], v[116:119]
	v_mfma_f32_16x16x32_bf16 v[104:107], v[174:177], v[198:201], v[104:107]
	v_mfma_f32_16x16x32_bf16 v[100:103], v[182:185], v[198:201], v[100:103]
	v_mfma_f32_16x16x32_bf16 v[88:91], v[174:177], v[206:209], v[88:91]
	v_mfma_f32_16x16x32_bf16 v[84:87], v[182:185], v[206:209], v[84:87]
	v_mfma_f32_16x16x32_bf16 v[72:75], v[174:177], v[214:217], v[72:75]
	v_mfma_f32_16x16x32_bf16 v[68:71], v[182:185], v[214:217], v[68:71]
	s_barrier
	s_add_i32 s14, s80, s0
	v_lshl_add_u64 v[218:219], s[56:57], 0, v[134:135]
	s_mov_b32 m0, s14
	ds_read_b128 v[186:189], v159 offset:16384
	ds_read_b128 v[190:193], v159 offset:17408
	ds_read_b128 v[194:197], v159 offset:18432
	ds_read_b128 v[198:201], v159 offset:19456
	ds_read_b128 v[202:205], v159 offset:20480
	ds_read_b128 v[206:209], v159 offset:21504
	ds_read_b128 v[210:213], v159 offset:22528
	ds_read_b128 v[214:217], v159 offset:23552
	global_load_lds_dwordx4 v[218:219], off
	s_add_i32 m0, s14, 0x2000
	s_add_u32 s94, s56, 0x80000
	v_lshl_add_u64 v[220:221], s[56:57], 0, v[138:139]
	s_addc_u32 s95, s57, 0
	s_add_i32 s14, s81, s0
	global_load_lds_dwordx4 v[220:221], off
	v_lshl_add_u64 v[2:3], s[94:95], 0, v[134:135]
	s_mov_b32 m0, s14
	v_lshl_add_u64 v[222:223], s[58:59], 0, v[132:133]
	global_load_lds_dwordx4 v[2:3], off
	v_lshl_add_u64 v[2:3], s[94:95], 0, v[138:139]
	s_add_i32 m0, s14, 0x2000
	v_lshl_add_u64 v[224:225], s[58:59], 0, v[136:137]
	global_load_lds_dwordx4 v[2:3], off
	s_mov_b32 m0, s9
	s_nop 0
	global_load_lds_dwordx4 v[222:223], off
	s_mov_b32 m0, s62
	s_nop 0
	global_load_lds_dwordx4 v[224:225], off
	s_waitcnt vmcnt(8)
	s_waitcnt lgkmcnt(0)
	s_barrier
	s_waitcnt lgkmcnt(0)
	v_mfma_f32_16x16x32_bf16 v[64:67], v[146:149], v[186:189], v[64:67]
	v_mfma_f32_16x16x32_bf16 v[60:63], v[162:165], v[186:189], v[60:63]
	v_mfma_f32_16x16x32_bf16 v[48:51], v[146:149], v[194:197], v[48:51]
	v_mfma_f32_16x16x32_bf16 v[44:47], v[162:165], v[194:197], v[44:47]
	v_mfma_f32_16x16x32_bf16 v[32:35], v[146:149], v[202:205], v[32:35]
	v_mfma_f32_16x16x32_bf16 v[28:31], v[162:165], v[202:205], v[28:31]
	v_mfma_f32_16x16x32_bf16 v[16:19], v[146:149], v[210:213], v[16:19]
	v_mfma_f32_16x16x32_bf16 v[12:15], v[162:165], v[210:213], v[12:15]
	v_mfma_f32_16x16x32_bf16 v[64:67], v[150:153], v[190:193], v[64:67]
	v_mfma_f32_16x16x32_bf16 v[60:63], v[166:169], v[190:193], v[60:63]
	v_mfma_f32_16x16x32_bf16 v[48:51], v[150:153], v[198:201], v[48:51]
	v_mfma_f32_16x16x32_bf16 v[44:47], v[166:169], v[198:201], v[44:47]
	v_mfma_f32_16x16x32_bf16 v[32:35], v[150:153], v[206:209], v[32:35]
	v_mfma_f32_16x16x32_bf16 v[28:31], v[166:169], v[206:209], v[28:31]
	v_mfma_f32_16x16x32_bf16 v[16:19], v[150:153], v[214:217], v[16:19]
	v_mfma_f32_16x16x32_bf16 v[12:15], v[166:169], v[214:217], v[12:15]
	v_mfma_f32_16x16x32_bf16 v[56:59], v[170:173], v[186:189], v[56:59]
	v_mfma_f32_16x16x32_bf16 v[52:55], v[178:181], v[186:189], v[52:55]
	v_mfma_f32_16x16x32_bf16 v[40:43], v[170:173], v[194:197], v[40:43]
	v_mfma_f32_16x16x32_bf16 v[36:39], v[178:181], v[194:197], v[36:39]
	v_mfma_f32_16x16x32_bf16 v[24:27], v[170:173], v[202:205], v[24:27]
	v_mfma_f32_16x16x32_bf16 v[20:23], v[178:181], v[202:205], v[20:23]
	v_mfma_f32_16x16x32_bf16 v[8:11], v[170:173], v[210:213], v[8:11]
	v_mfma_f32_16x16x32_bf16 v[2:5], v[178:181], v[210:213], v[4:7]
	v_mfma_f32_16x16x32_bf16 v[56:59], v[174:177], v[190:193], v[56:59]
	v_mfma_f32_16x16x32_bf16 v[52:55], v[182:185], v[190:193], v[52:55]
	v_mfma_f32_16x16x32_bf16 v[40:43], v[174:177], v[198:201], v[40:43]
	v_mfma_f32_16x16x32_bf16 v[36:39], v[182:185], v[198:201], v[36:39]
	v_mfma_f32_16x16x32_bf16 v[24:27], v[174:177], v[206:209], v[24:27]
	v_mfma_f32_16x16x32_bf16 v[20:23], v[182:185], v[206:209], v[20:23]
	v_mfma_f32_16x16x32_bf16 v[8:11], v[174:177], v[214:217], v[8:11]
	v_mfma_f32_16x16x32_bf16 v[2:5], v[182:185], v[214:217], v[2:5]
	s_barrier
	s_add_i32 s14, 0, 0x18000
	v_add_u32_e32 v1, s14, v155
	s_add_i32 s93, 0, 0x1c000
	ds_read_b128 v[146:149], v1
	ds_read_b128 v[150:153], v1 offset:1024
	ds_read_b128 v[162:165], v1 offset:2048
	ds_read_b128 v[166:169], v1 offset:3072
	v_add_u32_e32 v1, s93, v155
	ds_read_b128 v[170:173], v1
	ds_read_b128 v[174:177], v1 offset:1024
	ds_read_b128 v[178:181], v1 offset:2048
	ds_read_b128 v[182:185], v1 offset:3072
	s_add_u32 s58, s58, 0x40000
	s_addc_u32 s59, s59, 0
	s_mov_b32 m0, s63
	v_lshl_add_u64 v[6:7], s[58:59], 0, v[132:133]
	ds_read_b128 v[186:189], v159 offset:32768
	ds_read_b128 v[190:193], v159 offset:33792
	ds_read_b128 v[194:197], v159 offset:34816
	ds_read_b128 v[198:201], v159 offset:35840
	ds_read_b128 v[202:205], v159 offset:36864
	ds_read_b128 v[206:209], v159 offset:37888
	ds_read_b128 v[210:213], v159 offset:38912
	ds_read_b128 v[214:217], v159 offset:39936
	global_load_lds_dwordx4 v[6:7], off
	s_mov_b32 m0, s64
	v_lshl_add_u64 v[6:7], s[58:59], 0, v[136:137]
	global_load_lds_dwordx4 v[6:7], off
	s_waitcnt vmcnt(8)
	s_waitcnt lgkmcnt(0)
	s_barrier
	s_waitcnt lgkmcnt(0)
	v_mfma_f32_16x16x32_bf16 v[128:131], v[146:149], v[186:189], v[128:131]
	v_mfma_f32_16x16x32_bf16 v[124:127], v[162:165], v[186:189], v[124:127]
	v_mfma_f32_16x16x32_bf16 v[112:115], v[146:149], v[194:197], v[112:115]
	v_mfma_f32_16x16x32_bf16 v[108:111], v[162:165], v[194:197], v[108:111]
	v_mfma_f32_16x16x32_bf16 v[96:99], v[146:149], v[202:205], v[96:99]
	v_mfma_f32_16x16x32_bf16 v[92:95], v[162:165], v[202:205], v[92:95]
	v_mfma_f32_16x16x32_bf16 v[80:83], v[146:149], v[210:213], v[80:83]
	v_mfma_f32_16x16x32_bf16 v[76:79], v[162:165], v[210:213], v[76:79]
	v_mfma_f32_16x16x32_bf16 v[128:131], v[150:153], v[190:193], v[128:131]
	v_mfma_f32_16x16x32_bf16 v[124:127], v[166:169], v[190:193], v[124:127]
	v_mfma_f32_16x16x32_bf16 v[112:115], v[150:153], v[198:201], v[112:115]
	v_mfma_f32_16x16x32_bf16 v[108:111], v[166:169], v[198:201], v[108:111]
	v_mfma_f32_16x16x32_bf16 v[96:99], v[150:153], v[206:209], v[96:99]
	v_mfma_f32_16x16x32_bf16 v[92:95], v[166:169], v[206:209], v[92:95]
	v_mfma_f32_16x16x32_bf16 v[80:83], v[150:153], v[214:217], v[80:83]
	v_mfma_f32_16x16x32_bf16 v[76:79], v[166:169], v[214:217], v[76:79]
	v_mfma_f32_16x16x32_bf16 v[120:123], v[170:173], v[186:189], v[120:123]
	v_mfma_f32_16x16x32_bf16 v[116:119], v[178:181], v[186:189], v[116:119]
	v_mfma_f32_16x16x32_bf16 v[104:107], v[170:173], v[194:197], v[104:107]
	v_mfma_f32_16x16x32_bf16 v[100:103], v[178:181], v[194:197], v[100:103]
	v_mfma_f32_16x16x32_bf16 v[88:91], v[170:173], v[202:205], v[88:91]
	v_mfma_f32_16x16x32_bf16 v[84:87], v[178:181], v[202:205], v[84:87]
	v_mfma_f32_16x16x32_bf16 v[72:75], v[170:173], v[210:213], v[72:75]
	v_mfma_f32_16x16x32_bf16 v[68:71], v[178:181], v[210:213], v[68:71]
	v_mfma_f32_16x16x32_bf16 v[120:123], v[174:177], v[190:193], v[120:123]
	v_mfma_f32_16x16x32_bf16 v[116:119], v[182:185], v[190:193], v[116:119]
	v_mfma_f32_16x16x32_bf16 v[104:107], v[174:177], v[198:201], v[104:107]
	v_mfma_f32_16x16x32_bf16 v[100:103], v[182:185], v[198:201], v[100:103]
	v_mfma_f32_16x16x32_bf16 v[88:91], v[174:177], v[206:209], v[88:91]
	v_mfma_f32_16x16x32_bf16 v[84:87], v[182:185], v[206:209], v[84:87]
	v_mfma_f32_16x16x32_bf16 v[72:75], v[174:177], v[214:217], v[72:75]
	v_mfma_f32_16x16x32_bf16 v[68:71], v[182:185], v[214:217], v[68:71]
	s_barrier
	s_add_i32 s14, s14, s0
	v_lshl_add_u64 v[6:7], v[218:219], 0, s[24:25]
	s_mov_b32 m0, s14
	ds_read_b128 v[186:189], v159 offset:49152
	ds_read_b128 v[190:193], v159 offset:50176
	ds_read_b128 v[194:197], v159 offset:51200
	ds_read_b128 v[198:201], v159 offset:52224
	ds_read_b128 v[202:205], v159 offset:53248
	ds_read_b128 v[206:209], v159 offset:54272
	ds_read_b128 v[210:213], v159 offset:55296
	ds_read_b128 v[214:217], v159 offset:56320
	global_load_lds_dwordx4 v[6:7], off
	s_add_i32 m0, s14, 0x2000
	s_add_u32 s56, s56, 0x80080
	v_lshl_add_u64 v[6:7], v[220:221], 0, s[24:25]
	s_addc_u32 s57, s57, 0
	s_add_i32 s14, s93, s0
	global_load_lds_dwordx4 v[6:7], off
	s_mov_b32 m0, s14
	v_lshl_add_u64 v[6:7], s[56:57], 0, v[134:135]
	global_load_lds_dwordx4 v[6:7], off
	s_add_i32 m0, s14, 0x2000
	v_lshl_add_u64 v[6:7], s[56:57], 0, v[138:139]
	global_load_lds_dwordx4 v[6:7], off
	s_mov_b32 m0, s72
	v_lshl_add_u64 v[6:7], v[222:223], 0, s[24:25]
	global_load_lds_dwordx4 v[6:7], off
	s_mov_b32 m0, s73
	v_lshl_add_u64 v[6:7], v[224:225], 0, s[24:25]
	global_load_lds_dwordx4 v[6:7], off
	s_waitcnt vmcnt(8)
	s_waitcnt lgkmcnt(0)
	s_barrier
	s_waitcnt lgkmcnt(0)
	v_mfma_f32_16x16x32_bf16 v[64:67], v[146:149], v[186:189], v[64:67]
	v_mfma_f32_16x16x32_bf16 v[60:63], v[162:165], v[186:189], v[60:63]
	v_mfma_f32_16x16x32_bf16 v[48:51], v[146:149], v[194:197], v[48:51]
	v_mfma_f32_16x16x32_bf16 v[44:47], v[162:165], v[194:197], v[44:47]
	v_mfma_f32_16x16x32_bf16 v[32:35], v[146:149], v[202:205], v[32:35]
	v_mfma_f32_16x16x32_bf16 v[28:31], v[162:165], v[202:205], v[28:31]
	v_mfma_f32_16x16x32_bf16 v[16:19], v[146:149], v[210:213], v[16:19]
	v_mfma_f32_16x16x32_bf16 v[12:15], v[162:165], v[210:213], v[12:15]
	v_mfma_f32_16x16x32_bf16 v[64:67], v[150:153], v[190:193], v[64:67]
	v_mfma_f32_16x16x32_bf16 v[60:63], v[166:169], v[190:193], v[60:63]
	v_mfma_f32_16x16x32_bf16 v[48:51], v[150:153], v[198:201], v[48:51]
	v_mfma_f32_16x16x32_bf16 v[44:47], v[166:169], v[198:201], v[44:47]
	v_mfma_f32_16x16x32_bf16 v[32:35], v[150:153], v[206:209], v[32:35]
	v_mfma_f32_16x16x32_bf16 v[28:31], v[166:169], v[206:209], v[28:31]
	v_mfma_f32_16x16x32_bf16 v[16:19], v[150:153], v[214:217], v[16:19]
	v_mfma_f32_16x16x32_bf16 v[12:15], v[166:169], v[214:217], v[12:15]
	v_mfma_f32_16x16x32_bf16 v[56:59], v[170:173], v[186:189], v[56:59]
	v_mfma_f32_16x16x32_bf16 v[52:55], v[178:181], v[186:189], v[52:55]
	v_mfma_f32_16x16x32_bf16 v[40:43], v[170:173], v[194:197], v[40:43]
	v_mfma_f32_16x16x32_bf16 v[36:39], v[178:181], v[194:197], v[36:39]
	v_mfma_f32_16x16x32_bf16 v[24:27], v[170:173], v[202:205], v[24:27]
	v_mfma_f32_16x16x32_bf16 v[20:23], v[178:181], v[202:205], v[20:23]
	v_mfma_f32_16x16x32_bf16 v[6:9], v[170:173], v[210:213], v[8:11]
	v_mfma_f32_16x16x32_bf16 v[2:5], v[178:181], v[210:213], v[2:5]
	v_mfma_f32_16x16x32_bf16 v[56:59], v[174:177], v[190:193], v[56:59]
	v_mfma_f32_16x16x32_bf16 v[52:55], v[182:185], v[190:193], v[52:55]
	v_mfma_f32_16x16x32_bf16 v[40:43], v[174:177], v[198:201], v[40:43]
	v_mfma_f32_16x16x32_bf16 v[36:39], v[182:185], v[198:201], v[36:39]
	v_mfma_f32_16x16x32_bf16 v[24:27], v[174:177], v[206:209], v[24:27]
	v_mfma_f32_16x16x32_bf16 v[20:23], v[182:185], v[206:209], v[20:23]
	v_mfma_f32_16x16x32_bf16 v[8:11], v[174:177], v[214:217], v[6:9]
	v_mfma_f32_16x16x32_bf16 v[4:7], v[182:185], v[214:217], v[2:5]
	s_barrier
	s_add_i32 s14, s92, 2
	s_add_u32 s54, s54, 0x100
	s_addc_u32 s55, s55, 0
	s_add_u32 s90, s90, 0x100
	s_addc_u32 s91, s91, 0
	s_cmp_gt_u32 s92, 29
	s_mov_b32 s92, s14
	s_cbranch_scc1 .LBB0_554

.LBB0_658:
	v_add_u32_e32 v1, s61, v201
	ds_read_b128 v[102:105], v1
	ds_read_b128 v[106:109], v1 offset:1024
	ds_read_b128 v[110:113], v1 offset:2048
	ds_read_b128 v[114:117], v1 offset:3072
	v_add_u32_e32 v1, s62, v201
	ds_read_b128 v[118:121], v1
	ds_read_b128 v[156:159], v1 offset:1024
	ds_read_b128 v[160:163], v1 offset:2048
	ds_read_b128 v[164:167], v1 offset:3072
	s_and_b64 s[48:49], exec, s[48:49]
	s_cselect_b32 s49, s27, s78
	s_cselect_b32 s48, s29, s73
	s_add_u32 s80, s80, 0x40000
	s_addc_u32 s81, s81, 0
	v_lshl_add_u64 v[2:3], s[80:81], 0, v[178:179]
	s_add_i32 m0, s41, 0xc000
	ds_read_b128 v[168:171], v207
	ds_read_b128 v[184:187], v207 offset:1024
	ds_read_b128 v[188:191], v207 offset:2048
	ds_read_b128 v[192:195], v207 offset:3072
	ds_read_b128 v[208:211], v207 offset:4096
	ds_read_b128 v[212:215], v207 offset:5120
	ds_read_b128 v[216:219], v207 offset:6144
	ds_read_b128 v[220:223], v207 offset:7168
	global_load_lds_dwordx4 v[2:3], off
	s_add_i32 m0, s41, 0xe000
	v_lshl_add_u64 v[2:3], s[80:81], 0, v[174:175]
	global_load_lds_dwordx4 v[2:3], off
	s_waitcnt vmcnt(8)
	s_waitcnt lgkmcnt(0)
	s_barrier
	s_waitcnt lgkmcnt(0)
	v_mfma_f32_16x16x32_bf16 v[152:155], v[102:105], v[168:171], v[152:155]
	v_mfma_f32_16x16x32_bf16 v[148:151], v[110:113], v[168:171], v[148:151]
	v_mfma_f32_16x16x32_bf16 v[144:147], v[102:105], v[188:191], v[144:147]
	v_mfma_f32_16x16x32_bf16 v[140:143], v[110:113], v[188:191], v[140:143]
	v_mfma_f32_16x16x32_bf16 v[136:139], v[102:105], v[208:211], v[136:139]
	v_mfma_f32_16x16x32_bf16 v[132:135], v[110:113], v[208:211], v[132:135]
	v_mfma_f32_16x16x32_bf16 v[128:131], v[102:105], v[216:219], v[128:131]
	v_mfma_f32_16x16x32_bf16 v[122:125], v[110:113], v[216:219], v[124:127]
	v_mfma_f32_16x16x32_bf16 v[152:155], v[106:109], v[184:187], v[152:155]
	v_mfma_f32_16x16x32_bf16 v[148:151], v[114:117], v[184:187], v[148:151]
	v_mfma_f32_16x16x32_bf16 v[144:147], v[106:109], v[192:195], v[144:147]
	v_mfma_f32_16x16x32_bf16 v[140:143], v[114:117], v[192:195], v[140:143]
	v_mfma_f32_16x16x32_bf16 v[136:139], v[106:109], v[212:215], v[136:139]
	v_mfma_f32_16x16x32_bf16 v[132:135], v[114:117], v[212:215], v[132:135]
	v_mfma_f32_16x16x32_bf16 v[128:131], v[106:109], v[220:223], v[128:131]
	v_mfma_f32_16x16x32_bf16 v[122:125], v[114:117], v[220:223], v[122:125]
	v_mfma_f32_16x16x32_bf16 v[64:67], v[118:121], v[168:171], v[64:67]
	v_mfma_f32_16x16x32_bf16 v[60:63], v[160:163], v[168:171], v[60:63]
	v_mfma_f32_16x16x32_bf16 v[56:59], v[118:121], v[188:191], v[56:59]
	v_mfma_f32_16x16x32_bf16 v[52:55], v[160:163], v[188:191], v[52:55]
	v_mfma_f32_16x16x32_bf16 v[48:51], v[118:121], v[208:211], v[48:51]
	v_mfma_f32_16x16x32_bf16 v[44:47], v[160:163], v[208:211], v[44:47]
	v_mfma_f32_16x16x32_bf16 v[40:43], v[118:121], v[216:219], v[40:43]
	v_mfma_f32_16x16x32_bf16 v[36:39], v[160:163], v[216:219], v[36:39]
	v_mfma_f32_16x16x32_bf16 v[64:67], v[156:159], v[184:187], v[64:67]
	v_mfma_f32_16x16x32_bf16 v[60:63], v[164:167], v[184:187], v[60:63]
	v_mfma_f32_16x16x32_bf16 v[56:59], v[156:159], v[192:195], v[56:59]
	v_mfma_f32_16x16x32_bf16 v[52:55], v[164:167], v[192:195], v[52:55]
	v_mfma_f32_16x16x32_bf16 v[48:51], v[156:159], v[212:215], v[48:51]
	v_mfma_f32_16x16x32_bf16 v[44:47], v[164:167], v[212:215], v[44:47]
	v_mfma_f32_16x16x32_bf16 v[40:43], v[156:159], v[220:223], v[40:43]
	v_mfma_f32_16x16x32_bf16 v[36:39], v[164:167], v[220:223], v[36:39]
	s_barrier
	s_add_i32 s6, s61, s53
	v_lshl_add_u64 v[196:197], s[48:49], 0, v[176:177]
	s_mov_b32 m0, s6
	ds_read_b128 v[168:171], v207 offset:16384
	ds_read_b128 v[184:187], v207 offset:17408
	ds_read_b128 v[188:191], v207 offset:18432
	ds_read_b128 v[192:195], v207 offset:19456
	ds_read_b128 v[208:211], v207 offset:20480
	ds_read_b128 v[212:215], v207 offset:21504
	ds_read_b128 v[216:219], v207 offset:22528
	ds_read_b128 v[220:223], v207 offset:23552
	global_load_lds_dwordx4 v[196:197], off
	s_add_i32 m0, s6, 0x2000
	s_add_u32 s80, s48, 0x80000
	v_lshl_add_u64 v[224:225], s[48:49], 0, v[172:173]
	s_addc_u32 s81, s49, 0
	s_add_i32 s6, s62, s53
	global_load_lds_dwordx4 v[224:225], off
	v_lshl_add_u64 v[2:3], s[80:81], 0, v[176:177]
	s_mov_b32 m0, s6
	v_lshl_add_u64 v[226:227], s[50:51], 0, v[178:179]
	global_load_lds_dwordx4 v[2:3], off
	v_lshl_add_u64 v[2:3], s[80:81], 0, v[172:173]
	s_add_i32 m0, s6, 0x2000
	v_lshl_add_u64 v[228:229], s[50:51], 0, v[174:175]
	global_load_lds_dwordx4 v[2:3], off
	s_mov_b32 m0, s41
	s_nop 0
	global_load_lds_dwordx4 v[226:227], off
	s_mov_b32 m0, s56
	s_nop 0
	global_load_lds_dwordx4 v[228:229], off
	s_waitcnt vmcnt(8)
	s_waitcnt lgkmcnt(0)
	s_barrier
	s_waitcnt lgkmcnt(0)
	v_mfma_f32_16x16x32_bf16 v[96:99], v[102:105], v[168:171], v[96:99]
	v_mfma_f32_16x16x32_bf16 v[92:95], v[110:113], v[168:171], v[92:95]
	v_mfma_f32_16x16x32_bf16 v[88:91], v[102:105], v[188:191], v[88:91]
	v_mfma_f32_16x16x32_bf16 v[84:87], v[110:113], v[188:191], v[84:87]
	v_mfma_f32_16x16x32_bf16 v[80:83], v[102:105], v[208:211], v[80:83]
	v_mfma_f32_16x16x32_bf16 v[76:79], v[110:113], v[208:211], v[76:79]
	v_mfma_f32_16x16x32_bf16 v[72:75], v[102:105], v[216:219], v[72:75]
	v_mfma_f32_16x16x32_bf16 v[68:71], v[110:113], v[216:219], v[68:71]
	v_mfma_f32_16x16x32_bf16 v[96:99], v[106:109], v[184:187], v[96:99]
	v_mfma_f32_16x16x32_bf16 v[92:95], v[114:117], v[184:187], v[92:95]
	v_mfma_f32_16x16x32_bf16 v[88:91], v[106:109], v[192:195], v[88:91]
	v_mfma_f32_16x16x32_bf16 v[84:87], v[114:117], v[192:195], v[84:87]
	v_mfma_f32_16x16x32_bf16 v[80:83], v[106:109], v[212:215], v[80:83]
	v_mfma_f32_16x16x32_bf16 v[76:79], v[114:117], v[212:215], v[76:79]
	v_mfma_f32_16x16x32_bf16 v[72:75], v[106:109], v[220:223], v[72:75]
	v_mfma_f32_16x16x32_bf16 v[68:71], v[114:117], v[220:223], v[68:71]
	v_mfma_f32_16x16x32_bf16 v[32:35], v[118:121], v[168:171], v[32:35]
	v_mfma_f32_16x16x32_bf16 v[28:31], v[160:163], v[168:171], v[28:31]
	v_mfma_f32_16x16x32_bf16 v[24:27], v[118:121], v[188:191], v[24:27]
	v_mfma_f32_16x16x32_bf16 v[20:23], v[160:163], v[188:191], v[20:23]
	v_mfma_f32_16x16x32_bf16 v[16:19], v[118:121], v[208:211], v[16:19]
	v_mfma_f32_16x16x32_bf16 v[12:15], v[160:163], v[208:211], v[12:15]
	v_mfma_f32_16x16x32_bf16 v[8:11], v[118:121], v[216:219], v[8:11]
	v_mfma_f32_16x16x32_bf16 v[2:5], v[160:163], v[216:219], v[4:7]
	v_mfma_f32_16x16x32_bf16 v[32:35], v[156:159], v[184:187], v[32:35]
	v_mfma_f32_16x16x32_bf16 v[28:31], v[164:167], v[184:187], v[28:31]
	v_mfma_f32_16x16x32_bf16 v[24:27], v[156:159], v[192:195], v[24:27]
	v_mfma_f32_16x16x32_bf16 v[20:23], v[164:167], v[192:195], v[20:23]
	v_mfma_f32_16x16x32_bf16 v[16:19], v[156:159], v[212:215], v[16:19]
	v_mfma_f32_16x16x32_bf16 v[12:15], v[164:167], v[212:215], v[12:15]
	v_mfma_f32_16x16x32_bf16 v[8:11], v[156:159], v[220:223], v[8:11]
	v_mfma_f32_16x16x32_bf16 v[2:5], v[164:167], v[220:223], v[2:5]
	s_barrier
	s_add_i32 s6, 0, 0x18000
	v_add_u32_e32 v1, s6, v201
	s_add_i32 s80, 0, 0x1c000
	ds_read_b128 v[102:105], v1
	ds_read_b128 v[106:109], v1 offset:1024
	ds_read_b128 v[110:113], v1 offset:2048
	ds_read_b128 v[114:117], v1 offset:3072
	v_add_u32_e32 v1, s80, v201
	ds_read_b128 v[118:121], v1
	ds_read_b128 v[156:159], v1 offset:1024
	ds_read_b128 v[160:163], v1 offset:2048
	ds_read_b128 v[164:167], v1 offset:3072
	s_add_u32 s50, s50, 0x40000
	s_addc_u32 s51, s51, 0
	s_mov_b32 m0, s57
	v_lshl_add_u64 v[6:7], s[50:51], 0, v[178:179]
	ds_read_b128 v[168:171], v207 offset:32768
	ds_read_b128 v[184:187], v207 offset:33792
	ds_read_b128 v[188:191], v207 offset:34816
	ds_read_b128 v[192:195], v207 offset:35840
	ds_read_b128 v[208:211], v207 offset:36864
	ds_read_b128 v[212:215], v207 offset:37888
	ds_read_b128 v[216:219], v207 offset:38912
	ds_read_b128 v[220:223], v207 offset:39936
	global_load_lds_dwordx4 v[6:7], off
	s_mov_b32 m0, s58
	v_lshl_add_u64 v[6:7], s[50:51], 0, v[174:175]
	global_load_lds_dwordx4 v[6:7], off
	s_waitcnt vmcnt(8)
	s_waitcnt lgkmcnt(0)
	s_barrier
	s_waitcnt lgkmcnt(0)
	v_mfma_f32_16x16x32_bf16 v[152:155], v[102:105], v[168:171], v[152:155]
	v_mfma_f32_16x16x32_bf16 v[148:151], v[110:113], v[168:171], v[148:151]
	v_mfma_f32_16x16x32_bf16 v[144:147], v[102:105], v[188:191], v[144:147]
	v_mfma_f32_16x16x32_bf16 v[140:143], v[110:113], v[188:191], v[140:143]
	v_mfma_f32_16x16x32_bf16 v[136:139], v[102:105], v[208:211], v[136:139]
	v_mfma_f32_16x16x32_bf16 v[132:135], v[110:113], v[208:211], v[132:135]
	v_mfma_f32_16x16x32_bf16 v[126:129], v[102:105], v[216:219], v[128:131]
	v_mfma_f32_16x16x32_bf16 v[122:125], v[110:113], v[216:219], v[122:125]
	v_mfma_f32_16x16x32_bf16 v[152:155], v[106:109], v[184:187], v[152:155]
	v_mfma_f32_16x16x32_bf16 v[148:151], v[114:117], v[184:187], v[148:151]
	v_mfma_f32_16x16x32_bf16 v[144:147], v[106:109], v[192:195], v[144:147]
	v_mfma_f32_16x16x32_bf16 v[140:143], v[114:117], v[192:195], v[140:143]
	v_mfma_f32_16x16x32_bf16 v[136:139], v[106:109], v[212:215], v[136:139]
	v_mfma_f32_16x16x32_bf16 v[132:135], v[114:117], v[212:215], v[132:135]
	v_mfma_f32_16x16x32_bf16 v[128:131], v[106:109], v[220:223], v[126:129]
	v_mfma_f32_16x16x32_bf16 v[124:127], v[114:117], v[220:223], v[122:125]
	v_mfma_f32_16x16x32_bf16 v[64:67], v[118:121], v[168:171], v[64:67]
	v_mfma_f32_16x16x32_bf16 v[60:63], v[160:163], v[168:171], v[60:63]
	v_mfma_f32_16x16x32_bf16 v[56:59], v[118:121], v[188:191], v[56:59]
	v_mfma_f32_16x16x32_bf16 v[52:55], v[160:163], v[188:191], v[52:55]
	v_mfma_f32_16x16x32_bf16 v[48:51], v[118:121], v[208:211], v[48:51]
	v_mfma_f32_16x16x32_bf16 v[44:47], v[160:163], v[208:211], v[44:47]
	v_mfma_f32_16x16x32_bf16 v[40:43], v[118:121], v[216:219], v[40:43]
	v_mfma_f32_16x16x32_bf16 v[36:39], v[160:163], v[216:219], v[36:39]
	v_mfma_f32_16x16x32_bf16 v[64:67], v[156:159], v[184:187], v[64:67]
	v_mfma_f32_16x16x32_bf16 v[60:63], v[164:167], v[184:187], v[60:63]
	v_mfma_f32_16x16x32_bf16 v[56:59], v[156:159], v[192:195], v[56:59]
	v_mfma_f32_16x16x32_bf16 v[52:55], v[164:167], v[192:195], v[52:55]
	v_mfma_f32_16x16x32_bf16 v[48:51], v[156:159], v[212:215], v[48:51]
	v_mfma_f32_16x16x32_bf16 v[44:47], v[164:167], v[212:215], v[44:47]
	v_mfma_f32_16x16x32_bf16 v[40:43], v[156:159], v[220:223], v[40:43]
	v_mfma_f32_16x16x32_bf16 v[36:39], v[164:167], v[220:223], v[36:39]
	s_barrier
	s_add_i32 s6, s6, s53
	v_lshl_add_u64 v[6:7], v[196:197], 0, s[14:15]
	s_mov_b32 m0, s6
	ds_read_b128 v[168:171], v207 offset:49152
	ds_read_b128 v[184:187], v207 offset:50176
	ds_read_b128 v[188:191], v207 offset:51200
	ds_read_b128 v[192:195], v207 offset:52224
	ds_read_b128 v[208:211], v207 offset:53248
	ds_read_b128 v[212:215], v207 offset:54272
	ds_read_b128 v[216:219], v207 offset:55296
	ds_read_b128 v[220:223], v207 offset:56320
	global_load_lds_dwordx4 v[6:7], off
	s_add_i32 m0, s6, 0x2000
	s_add_u32 s48, s48, 0x80080
	v_lshl_add_u64 v[6:7], v[224:225], 0, s[14:15]
	s_addc_u32 s49, s49, 0
	s_add_i32 s6, s80, s53
	global_load_lds_dwordx4 v[6:7], off
	s_mov_b32 m0, s6
	v_lshl_add_u64 v[6:7], s[48:49], 0, v[176:177]
	global_load_lds_dwordx4 v[6:7], off
	s_add_i32 m0, s6, 0x2000
	v_lshl_add_u64 v[6:7], s[48:49], 0, v[172:173]
	global_load_lds_dwordx4 v[6:7], off
	s_mov_b32 m0, s59
	v_lshl_add_u64 v[6:7], v[226:227], 0, s[14:15]
	global_load_lds_dwordx4 v[6:7], off
	s_mov_b32 m0, s60
	v_lshl_add_u64 v[6:7], v[228:229], 0, s[14:15]
	global_load_lds_dwordx4 v[6:7], off
	s_waitcnt vmcnt(8)
	s_waitcnt lgkmcnt(0)
	s_barrier
	s_waitcnt lgkmcnt(0)
	v_mfma_f32_16x16x32_bf16 v[96:99], v[102:105], v[168:171], v[96:99]
	v_mfma_f32_16x16x32_bf16 v[92:95], v[110:113], v[168:171], v[92:95]
	v_mfma_f32_16x16x32_bf16 v[88:91], v[102:105], v[188:191], v[88:91]
	v_mfma_f32_16x16x32_bf16 v[84:87], v[110:113], v[188:191], v[84:87]
	v_mfma_f32_16x16x32_bf16 v[80:83], v[102:105], v[208:211], v[80:83]
	v_mfma_f32_16x16x32_bf16 v[76:79], v[110:113], v[208:211], v[76:79]
	v_mfma_f32_16x16x32_bf16 v[72:75], v[102:105], v[216:219], v[72:75]
	v_mfma_f32_16x16x32_bf16 v[68:71], v[110:113], v[216:219], v[68:71]
	v_mfma_f32_16x16x32_bf16 v[96:99], v[106:109], v[184:187], v[96:99]
	v_mfma_f32_16x16x32_bf16 v[92:95], v[114:117], v[184:187], v[92:95]
	v_mfma_f32_16x16x32_bf16 v[88:91], v[106:109], v[192:195], v[88:91]
	v_mfma_f32_16x16x32_bf16 v[84:87], v[114:117], v[192:195], v[84:87]
	v_mfma_f32_16x16x32_bf16 v[80:83], v[106:109], v[212:215], v[80:83]
	v_mfma_f32_16x16x32_bf16 v[76:79], v[114:117], v[212:215], v[76:79]
	v_mfma_f32_16x16x32_bf16 v[72:75], v[106:109], v[220:223], v[72:75]
	v_mfma_f32_16x16x32_bf16 v[68:71], v[114:117], v[220:223], v[68:71]
	v_mfma_f32_16x16x32_bf16 v[32:35], v[118:121], v[168:171], v[32:35]
	v_mfma_f32_16x16x32_bf16 v[28:31], v[160:163], v[168:171], v[28:31]
	v_mfma_f32_16x16x32_bf16 v[24:27], v[118:121], v[188:191], v[24:27]
	v_mfma_f32_16x16x32_bf16 v[20:23], v[160:163], v[188:191], v[20:23]
	v_mfma_f32_16x16x32_bf16 v[16:19], v[118:121], v[208:211], v[16:19]
	v_mfma_f32_16x16x32_bf16 v[12:15], v[160:163], v[208:211], v[12:15]
	v_mfma_f32_16x16x32_bf16 v[6:9], v[118:121], v[216:219], v[8:11]
	v_mfma_f32_16x16x32_bf16 v[2:5], v[160:163], v[216:219], v[2:5]
	v_mfma_f32_16x16x32_bf16 v[32:35], v[156:159], v[184:187], v[32:35]
	v_mfma_f32_16x16x32_bf16 v[28:31], v[164:167], v[184:187], v[28:31]
	v_mfma_f32_16x16x32_bf16 v[24:27], v[156:159], v[192:195], v[24:27]
	v_mfma_f32_16x16x32_bf16 v[20:23], v[164:167], v[192:195], v[20:23]
	v_mfma_f32_16x16x32_bf16 v[16:19], v[156:159], v[212:215], v[16:19]
	v_mfma_f32_16x16x32_bf16 v[12:15], v[164:167], v[212:215], v[12:15]
	v_mfma_f32_16x16x32_bf16 v[8:11], v[156:159], v[220:223], v[6:9]
	v_mfma_f32_16x16x32_bf16 v[4:7], v[164:167], v[220:223], v[2:5]
	s_barrier
	s_add_i32 s6, s79, 2
	s_add_u32 s44, s44, 0x100
	s_addc_u32 s45, s45, 0
	s_add_u32 s73, s73, 0x100
	s_addc_u32 s78, s78, 0
	s_cmp_gt_u32 s79, 29
	s_cbranch_scc1 .LBB0_660
	s_mov_b32 s79, s6
	s_cmp_lg_u32 s79, 16
	s_cbranch_scc0 .LBB0_652
	s_branch .LBB0_653
